# all GEMM K loops (A, C0, C1, E1, and the A operand of E2) stage their bf16 tiles memory->LDS with global_load_lds_dwordx4 instead of registers + ds_write_b128
# speedup vs baseline: 1.0148x; 1.0096x over previous
; template <bool ABF, bool BBF, class RowF, class ColF, class Epi>
; __device__ __forceinline__ void gemm_tile(char* smem, int K, RowF rowptr, ColF colptr, int ldb, Epi epi) {
;     ...
; #pragma unroll
;   for (int i = 0; i < 4; i++)
; #pragma unroll
;     for (int j = 0; j < 4; j++) acc[i][j] = f32x4{0.f, 0.f, 0.f, 0.f};
;   constexpr int NA = ABF ? 4 : 8;
;   const int ar0 = ABF ? (tid >> 3) : (tid >> 4);
;   const int ac = ABF ? (tid & 7) * 8 : (tid & 15) * 4;
;   constexpr int ARS = ABF ? 32 : 16;
;   const char* ap[NA];
; #pragma unroll
;   for (int i = 0; i < NA; i++) ap[i] = (const char*)rowptr(ar0 + ARS * i) + ac * (ABF ? 2 : 4);
;   const int bc = tid & 127, kh = tid >> 7;
;   const float* bp = BBF ? nullptr : ((const float*)colptr(bc) + (size_t)(kh * 32) * ldb);
;   const int br0 = tid >> 3, bcc = (tid & 7) * 8;
;   const char* bq[4];
;   if (BBF) {
; #pragma unroll
;     for (int i = 0; i < 4; i++) bq[i] = (const char*)colptr(br0 + 32 * i) + bcc * 2;
;   }
;   u32x4 ra[NA];
;   float rb[BBF ? 1 : 32];
;   u32x4 rbb[BBF ? 4 : 1];
;   auto gload = [&](int k0) {
; #pragma unroll
;     for (int i = 0; i < NA; i++) ra[i] = *(const u32x4*)(ap[i] + (size_t)k0 * (ABF ? 2 : 4));
;     if (BBF) {
; #pragma unroll
;       for (int i = 0; i < 4; i++) rbb[BBF ? i : 0] = *(const u32x4*)(bq[i] + (size_t)k0 * 2);
;     } else {
;       const float* b = bp + (size_t)k0 * ldb;
; #pragma unroll
;       for (int j = 0; j < 32; j++) rb[BBF ? 0 : j] = b[(size_t)j * ldb];
;     }
;   };
; __device__ void phaseC(const Params& p, char* smem, int which) {
;     ...
;     const int mt = half ? ((q / 9) * 16 + 7 + q % 9) : ((q / 7) * 16 + q % 7), nt = j;
;     const int m0 = mt * 128, n0 = nt * 128;
;     auto rowf = [&](int r) { return (const void*)(p.O + (size_t)(m0 + r) * DM); };
;     auto colf = [&](int c) { return (const void*)(p.WoutT + (size_t)(n0 + c) * DM); };
.LBB0_898:
	s_or_b64 exec, exec, s[18:19]
	s_cmp_lg_u32 s33, -1
	s_cselect_b32 s6, s33, 0
	s_cselect_b32 s18, s1, 0
	v_mov_b32_e32 v0, s6
	v_mov_b32_e32 v1, s18
	s_waitcnt lgkmcnt(0)
	s_barrier
	flat_load_dword v0, v[0:1] sc0 sc1
	s_waitcnt vmcnt(0)
	s_mov_b64 s[20:21], -1
	s_waitcnt lgkmcnt(0)
	v_cmp_gt_i32_e32 vcc, 56, v0
	s_and_saveexec_b64 s[18:19], vcc
	s_cbranch_execz .LBB0_893
	v_mul_hi_i32 v1, v0, s29
	v_add_u32_e32 v1, v1, v0
	v_lshrrev_b32_e32 v2, 31, v1
	v_lshrrev_b32_e32 v1, 2, v1
	v_add_u32_e32 v1, v1, v2
	v_lshl_add_u32 v1, v1, 3, v1
	v_add_lshl_u32 v99, v1, v0, 7
	v_or_b32_e32 v0, v99, v160
	v_ashrrev_i32_e32 v1, 31, v0
	v_lshlrev_b64 v[2:3], 11, v[0:1]
	v_add_u32_e32 v6, 32, v0
	v_add_u32_e32 v10, 64, v0
	v_add_u32_e32 v0, 0x60, v0
	v_ashrrev_i32_e32 v7, 31, v6
	v_ashrrev_i32_e32 v11, 31, v10
	v_ashrrev_i32_e32 v1, 31, v0
	v_lshlrev_b64 v[6:7], 11, v[6:7]
	v_lshlrev_b64 v[10:11], 11, v[10:11]
	v_lshlrev_b64 v[0:1], 11, v[0:1]
	v_lshl_add_u64 v[4:5], v[106:107], 0, v[2:3]
	v_lshl_add_u64 v[8:9], v[106:107], 0, v[6:7]
	v_lshl_add_u64 v[12:13], v[106:107], 0, v[10:11]
	v_lshl_add_u64 v[14:15], v[106:107], 0, v[0:1]
	v_lshrrev_b32_e32 v78, 4, v128
	v_xor_b32_e32 v78, v78, v128
	v_and_b32_e32 v78, 7, v78
	v_lshlrev_b32_e32 v54, 4, v78
	v_mov_b32_e32 v55, 0
	v_sub_u32_e32 v58, v54, v124
	v_lshrrev_b32_e32 v78, 6, v128
	v_ashrrev_i32_e32 v59, 31, v58
	v_readfirstlane_b32 s100, v78
	s_lshl_b32 s100, s100, 10
	s_add_u32 m0, s100, 0x4000
	v_lshl_add_u64 v[70:71], v[114:115], 0, v[58:59]
	global_load_lds_dwordx4 v[70:71], off
	s_add_u32 m0, s100, 0x5000
	v_lshl_add_u64 v[70:71], v[116:117], 0, v[58:59]
	global_load_lds_dwordx4 v[70:71], off
	s_add_u32 m0, s100, 0x6000
	v_lshl_add_u64 v[70:71], v[118:119], 0, v[58:59]
	global_load_lds_dwordx4 v[70:71], off
	s_add_u32 m0, s100, 0x7000
	v_lshl_add_u64 v[70:71], v[120:121], 0, v[58:59]
	global_load_lds_dwordx4 v[70:71], off
	s_add_u32 m0, s100, 0x0
	v_lshl_add_u64 v[70:71], v[4:5], 0, v[58:59]
	global_load_lds_dwordx4 v[70:71], off
	s_add_u32 m0, s100, 0x1000
	v_lshl_add_u64 v[70:71], v[8:9], 0, v[58:59]
	global_load_lds_dwordx4 v[70:71], off
	s_add_u32 m0, s100, 0x2000
	v_lshl_add_u64 v[70:71], v[12:13], 0, v[58:59]
	global_load_lds_dwordx4 v[70:71], off
	s_add_u32 m0, s100, 0x3000
	v_lshl_add_u64 v[70:71], v[14:15], 0, v[58:59]
	global_load_lds_dwordx4 v[70:71], off
	v_mov_b32_e32 v60, 0
	s_mov_b32 s6, 0
	v_mov_b64_e32 v[140:141], v[110:111]
	s_mov_b32 s37, 0
	v_mov_b32_e32 v61, v60
	v_mov_b32_e32 v62, v60
	v_mov_b32_e32 v63, v60
	v_mov_b32_e32 v84, v60
	v_mov_b32_e32 v85, v60
	v_mov_b32_e32 v86, v60
	v_mov_b32_e32 v87, v60
	v_mov_b32_e32 v64, v60
	v_mov_b32_e32 v65, v60
	v_mov_b32_e32 v66, v60
	v_mov_b32_e32 v67, v60
	v_mov_b32_e32 v48, v60
	v_mov_b32_e32 v49, v60
	v_mov_b32_e32 v50, v60
	v_mov_b32_e32 v51, v60
	v_mov_b32_e32 v44, v60
	v_mov_b32_e32 v45, v60
	v_mov_b32_e32 v46, v60
	v_mov_b32_e32 v47, v60
	v_mov_b32_e32 v40, v60
	v_mov_b32_e32 v41, v60
	v_mov_b32_e32 v42, v60
	v_mov_b32_e32 v43, v60
	v_mov_b32_e32 v36, v60
	v_mov_b32_e32 v37, v60
	v_mov_b32_e32 v38, v60
	v_mov_b32_e32 v39, v60
	v_mov_b32_e32 v32, v60
	v_mov_b32_e32 v33, v60
	v_mov_b32_e32 v34, v60
	v_mov_b32_e32 v35, v60
	v_mov_b32_e32 v28, v60
	v_mov_b32_e32 v29, v60
	v_mov_b32_e32 v30, v60
	v_mov_b32_e32 v31, v60
	v_mov_b32_e32 v24, v60
	v_mov_b32_e32 v25, v60
	v_mov_b32_e32 v26, v60
	v_mov_b32_e32 v27, v60
	v_mov_b32_e32 v20, v60
	v_mov_b32_e32 v21, v60
	v_mov_b32_e32 v22, v60
	v_lshl_add_u64 v[142:143], s[4:5], 0, v[2:3]
	v_lshl_add_u64 v[144:145], s[4:5], 0, v[6:7]
	v_lshl_add_u64 v[146:147], s[4:5], 0, v[10:11]
	v_lshl_add_u64 v[148:149], s[4:5], 0, v[0:1]
	v_mov_b32_e32 v23, v60
	v_mov_b32_e32 v16, v60
	v_mov_b32_e32 v17, v60
	v_mov_b32_e32 v18, v60
	v_mov_b32_e32 v19, v60
	v_mov_b32_e32 v12, v60
	v_mov_b32_e32 v13, v60
	v_mov_b32_e32 v14, v60
	v_mov_b32_e32 v15, v60
	v_mov_b32_e32 v8, v60
	v_mov_b32_e32 v9, v60
	v_mov_b32_e32 v10, v60
	v_mov_b32_e32 v11, v60
	v_mov_b32_e32 v4, v60
	v_mov_b32_e32 v5, v60
	v_mov_b32_e32 v6, v60
	v_mov_b32_e32 v7, v60
	v_mov_b32_e32 v0, v60
	v_mov_b32_e32 v1, v60
	v_mov_b32_e32 v2, v60
	v_mov_b32_e32 v3, v60
	s_waitcnt vmcnt(0)
	s_waitcnt lgkmcnt(0)
	s_barrier
	s_branch .LBB0_901

; template <bool ABF, bool BBF, class RowF, class ColF, class Epi>
; __device__ __forceinline__ void gemm_tile(char* smem, int K, RowF rowptr, ColF colptr, int ldb, Epi epi) {
;     ...
;   for (int k0 = 0; k0 < K; k0 += BK) {
;     if (k0 + BK < K) gload(k0 + BK);
;     const u16* As = As0 + cur * (GEMM_SMEM / 2);
;     const u16* Bs = As + BM * LDT;
;     {
;       bf16x8 af[2][4], bfr[2][4];
; #pragma unroll
;       for (int ks = 0; ks < 2; ks++) {
; #pragma unroll
;         for (int mi = 0; mi < 4; mi++) af[ks][mi] = *(const bf16x8*)&As[(wm * 64 + mi * 16 + l15) * LDT + (((ks * 4 + kg) ^ swz) << 3)];
; #pragma unroll
;         for (int ni = 0; ni < 4; ni++) bfr[ks][ni] = *(const bf16x8*)&Bs[(wn * 64 + ni * 16 + l15) * LDT + (((ks * 4 + kg) ^ swz) << 3)];
;       }
;       __builtin_amdgcn_sched_barrier(0);
; #pragma unroll
;       for (int ks = 0; ks < 2; ks++)
; #pragma unroll
;         for (int mi = 0; mi < 4; mi++)
; #pragma unroll
;           for (int ni = 0; ni < 4; ni++)
;             acc[mi][ni] = __builtin_amdgcn_mfma_f32_16x16x32_bf16(bfr[ks][ni], af[ks][mi], acc[mi][ni], 0, 0, 0);
;       __builtin_amdgcn_sched_barrier(0);
;     }
;     if (k0 + BK < K) sstore(cur ^ 1);
;     __syncthreads();
;     cur ^= 1;
;   }
.LBB0_901:
	s_cmpk_lt_u32 s6, 0x3c0
	s_cselect_b64 s[22:23], -1, 0
	s_cmpk_gt_u32 s6, 0x3bf
	s_cselect_b64 s[20:21], -1, 0
	s_and_b64 vcc, exec, s[20:21]
	s_cbranch_vccnz .LBB0_903
	s_xor_b32 s101, s37, 1
	s_lshl_b32 s101, s101, 15
	s_add_u32 s101, s101, s100
	s_waitcnt vmcnt(1)
	v_lshl_add_u64 v[88:89], v[140:141], 0, v[54:55]
	v_add_co_u32_e32 v80, vcc, 0x10000, v88
	v_lshl_add_u64 v[52:53], v[142:143], 0, v[54:55]
	s_nop 0
	v_addc_co_u32_e32 v81, vcc, 0, v89, vcc
	v_add_co_u32_e32 v90, vcc, 0x20000, v88
	v_lshl_add_u64 v[56:57], v[144:145], 0, v[54:55]
	s_nop 0
	v_addc_co_u32_e32 v91, vcc, 0, v89, vcc
	s_waitcnt vmcnt(0)
	v_add_co_u32_e32 v92, vcc, 0x30000, v88
	v_lshl_add_u64 v[68:69], v[146:147], 0, v[54:55]
	v_lshl_add_u64 v[72:73], v[148:149], 0, v[54:55]
	v_addc_co_u32_e32 v93, vcc, 0, v89, vcc
	s_add_u32 m0, s101, 0x0
	s_nop 0
	global_load_lds_dwordx4 v[52:53], off
	s_nop 0
	s_add_u32 m0, s101, 0x1000
	s_nop 0
	global_load_lds_dwordx4 v[56:57], off
	s_nop 0
	s_add_u32 m0, s101, 0x2000
	s_nop 0
	global_load_lds_dwordx4 v[68:69], off
	s_nop 0
	s_add_u32 m0, s101, 0x3000
	s_nop 0
	global_load_lds_dwordx4 v[72:73], off
	s_nop 0
	s_add_u32 m0, s101, 0x4000
	v_lshl_add_u64 v[88:89], v[88:89], 0, s[2:3]
	global_load_lds_dwordx4 v[88:89], off
	s_nop 0
	s_add_u32 m0, s101, 0x5000
	v_lshl_add_u64 v[80:81], v[80:81], 0, s[2:3]
	global_load_lds_dwordx4 v[80:81], off
	s_nop 0
	s_add_u32 m0, s101, 0x6000
	v_lshl_add_u64 v[90:91], v[90:91], 0, s[2:3]
	global_load_lds_dwordx4 v[90:91], off
	s_nop 0
	s_add_u32 m0, s101, 0x7000
	v_lshl_add_u64 v[92:93], v[92:93], 0, s[2:3]
	global_load_lds_dwordx4 v[92:93], off
.LBB0_903:
	s_lshl_b32 s38, s37, 15
	s_add_i32 s38, s38, 0
	v_lshlrev_b32_e32 v101, 1, v163
	v_lshlrev_b32_e32 v102, 1, v164
	v_add3_u32 v139, s38, v101, v102
	v_add3_u32 v158, s38, v102, v101
	ds_read_b128 v[150:153], v139
	ds_read_b128 v[154:157], v158 offset:2048
	ds_read_b128 v[172:175], v158 offset:4096
	ds_read_b128 v[176:179], v158 offset:6144
	v_lshlrev_b32_e32 v139, 1, v162
	v_add_u32_e32 v158, s38, v139
	v_add_u32_e32 v101, v158, v101
	ds_read_b128 v[180:183], v101 offset:16384
	ds_read_b128 v[184:187], v101 offset:18432
	ds_read_b128 v[188:191], v101 offset:20480
	ds_read_b128 v[192:195], v101 offset:22528
	v_lshlrev_b32_e32 v101, 1, v165
	v_add_u32_e32 v159, s38, v101
	v_add_u32_e32 v102, v159, v102
	ds_read_b128 v[196:199], v102
	ds_read_b128 v[200:203], v102 offset:2048
	ds_read_b128 v[204:207], v102 offset:4096
	ds_read_b128 v[208:211], v102 offset:6144
	v_add_u32_e32 v102, v159, v139
	v_add_u32_e32 v101, v158, v101
	ds_read_b128 v[212:215], v102 offset:16384
	ds_read_b128 v[216:219], v101 offset:18432
	ds_read_b128 v[220:223], v101 offset:20480
	ds_read_b128 v[224:227], v101 offset:22528
	s_waitcnt lgkmcnt(11)
	v_mfma_f32_16x16x32_bf16 v[60:63], v[180:183], v[150:153], v[60:63]
	s_waitcnt lgkmcnt(10)
	v_mfma_f32_16x16x32_bf16 v[84:87], v[184:187], v[150:153], v[84:87]
	s_waitcnt lgkmcnt(9)
	v_mfma_f32_16x16x32_bf16 v[64:67], v[188:191], v[150:153], v[64:67]
	s_waitcnt lgkmcnt(8)
	v_mfma_f32_16x16x32_bf16 v[48:51], v[192:195], v[150:153], v[48:51]
	v_mfma_f32_16x16x32_bf16 v[44:47], v[180:183], v[154:157], v[44:47]
	v_mfma_f32_16x16x32_bf16 v[40:43], v[184:187], v[154:157], v[40:43]
	v_mfma_f32_16x16x32_bf16 v[36:39], v[188:191], v[154:157], v[36:39]
	v_mfma_f32_16x16x32_bf16 v[32:35], v[192:195], v[154:157], v[32:35]
	v_mfma_f32_16x16x32_bf16 v[28:31], v[180:183], v[172:175], v[28:31]
	v_mfma_f32_16x16x32_bf16 v[24:27], v[184:187], v[172:175], v[24:27]
	v_mfma_f32_16x16x32_bf16 v[20:23], v[188:191], v[172:175], v[20:23]
	v_mfma_f32_16x16x32_bf16 v[16:19], v[192:195], v[172:175], v[16:19]
	v_mfma_f32_16x16x32_bf16 v[12:15], v[180:183], v[176:179], v[12:15]
	v_mfma_f32_16x16x32_bf16 v[8:11], v[184:187], v[176:179], v[8:11]
	v_mfma_f32_16x16x32_bf16 v[4:7], v[188:191], v[176:179], v[4:7]
	v_mfma_f32_16x16x32_bf16 v[0:3], v[192:195], v[176:179], v[0:3]
	s_waitcnt lgkmcnt(3)
	v_mfma_f32_16x16x32_bf16 v[60:63], v[212:215], v[196:199], v[60:63]
	s_waitcnt lgkmcnt(2)
	v_mfma_f32_16x16x32_bf16 v[84:87], v[216:219], v[196:199], v[84:87]
	s_waitcnt lgkmcnt(1)
	v_mfma_f32_16x16x32_bf16 v[64:67], v[220:223], v[196:199], v[64:67]
	s_waitcnt lgkmcnt(0)
	v_mfma_f32_16x16x32_bf16 v[48:51], v[224:227], v[196:199], v[48:51]
	v_mfma_f32_16x16x32_bf16 v[44:47], v[212:215], v[200:203], v[44:47]
	v_mfma_f32_16x16x32_bf16 v[40:43], v[216:219], v[200:203], v[40:43]
	v_mfma_f32_16x16x32_bf16 v[36:39], v[220:223], v[200:203], v[36:39]
	v_mfma_f32_16x16x32_bf16 v[32:35], v[224:227], v[200:203], v[32:35]
	v_mfma_f32_16x16x32_bf16 v[28:31], v[212:215], v[204:207], v[28:31]
	v_mfma_f32_16x16x32_bf16 v[24:27], v[216:219], v[204:207], v[24:27]
	v_mfma_f32_16x16x32_bf16 v[20:23], v[220:223], v[204:207], v[20:23]
	v_mfma_f32_16x16x32_bf16 v[16:19], v[224:227], v[204:207], v[16:19]
	v_mfma_f32_16x16x32_bf16 v[12:15], v[212:215], v[208:211], v[12:15]
	v_mfma_f32_16x16x32_bf16 v[8:11], v[216:219], v[208:211], v[8:11]
	v_mfma_f32_16x16x32_bf16 v[4:7], v[220:223], v[208:211], v[4:7]
	v_mfma_f32_16x16x32_bf16 v[0:3], v[224:227], v[208:211], v[0:3]
	s_andn2_b64 vcc, exec, s[22:23]
	s_cbranch_vccnz .LBB0_900
	s_waitcnt vmcnt(0)
	s_branch .LBB0_900

; template <bool ABF, bool BBF, class RowF, class ColF, class Epi>
; __device__ __forceinline__ void gemm_tile(char* smem, int K, RowF rowptr, ColF colptr, int ldb, Epi epi) {
;     ...
; #pragma unroll
;   for (int i = 0; i < 4; i++)
; #pragma unroll
;     for (int j = 0; j < 4; j++) acc[i][j] = f32x4{0.f, 0.f, 0.f, 0.f};
;   constexpr int NA = ABF ? 4 : 8;
;   const int ar0 = ABF ? (tid >> 3) : (tid >> 4);
;   const int ac = ABF ? (tid & 7) * 8 : (tid & 15) * 4;
;   constexpr int ARS = ABF ? 32 : 16;
;   const char* ap[NA];
; #pragma unroll
;   for (int i = 0; i < NA; i++) ap[i] = (const char*)rowptr(ar0 + ARS * i) + ac * (ABF ? 2 : 4);
;   const int bc = tid & 127, kh = tid >> 7;
;   const float* bp = BBF ? nullptr : ((const float*)colptr(bc) + (size_t)(kh * 32) * ldb);
;   const int br0 = tid >> 3, bcc = (tid & 7) * 8;
;   const char* bq[4];
;   if (BBF) {
; #pragma unroll
;     for (int i = 0; i < 4; i++) bq[i] = (const char*)colptr(br0 + 32 * i) + bcc * 2;
;   }
;   u32x4 ra[NA];
;   float rb[BBF ? 1 : 32];
;   u32x4 rbb[BBF ? 4 : 1];
;   auto gload = [&](int k0) {
; #pragma unroll
;     for (int i = 0; i < NA; i++) ra[i] = *(const u32x4*)(ap[i] + (size_t)k0 * (ABF ? 2 : 4));
;     if (BBF) {
; #pragma unroll
;       for (int i = 0; i < 4; i++) rbb[BBF ? i : 0] = *(const u32x4*)(bq[i] + (size_t)k0 * 2);
;     } else {
;       const float* b = bp + (size_t)k0 * ldb;
; #pragma unroll
;       for (int j = 0; j < 32; j++) rb[BBF ? 0 : j] = b[(size_t)j * ldb];
;     }
;   };
; __device__ void phaseC(const Params& p, char* smem, int which) {
;     ...
;     const int mt = half ? ((q / 9) * 16 + 7 + q % 9) : ((q / 7) * 16 + q % 7), nt = j;
;     const int m0 = mt * 128, n0 = nt * 128;
;     auto rowf = [&](int r) { return (const void*)(p.O + (size_t)(m0 + r) * DM); };
;     auto colf = [&](int c) { return (const void*)(p.WoutT + (size_t)(n0 + c) * DM); };
.LBB0_1039:
	v_lshlrev_b32_e32 v96, 7, v2
	v_or_b32_e32 v0, v96, v160
	v_ashrrev_i32_e32 v1, 31, v0
	v_lshlrev_b64 v[2:3], 11, v[0:1]
	v_add_u32_e32 v6, 32, v0
	v_add_u32_e32 v10, 64, v0
	v_add_u32_e32 v0, 0x60, v0
	v_ashrrev_i32_e32 v7, 31, v6
	v_ashrrev_i32_e32 v11, 31, v10
	v_ashrrev_i32_e32 v1, 31, v0
	v_lshlrev_b64 v[6:7], 11, v[6:7]
	v_lshlrev_b64 v[10:11], 11, v[10:11]
	v_lshlrev_b64 v[0:1], 11, v[0:1]
	v_lshl_add_u64 v[4:5], v[102:103], 0, v[2:3]
	v_lshl_add_u64 v[8:9], v[102:103], 0, v[6:7]
	v_lshl_add_u64 v[12:13], v[102:103], 0, v[10:11]
	v_lshl_add_u64 v[14:15], v[102:103], 0, v[0:1]
	v_lshrrev_b32_e32 v78, 4, v128
	v_xor_b32_e32 v78, v78, v128
	v_and_b32_e32 v78, 7, v78
	v_lshlrev_b32_e32 v66, 4, v78
	v_mov_b32_e32 v67, 0
	v_sub_u32_e32 v70, v66, v124
	v_lshrrev_b32_e32 v78, 6, v128
	v_ashrrev_i32_e32 v71, 31, v70
	v_readfirstlane_b32 s100, v78
	s_lshl_b32 s100, s100, 10
	s_add_u32 m0, s100, 0x4000
	v_lshl_add_u64 v[74:75], v[112:113], 0, v[70:71]
	global_load_lds_dwordx4 v[74:75], off
	s_add_u32 m0, s100, 0x5000
	v_lshl_add_u64 v[74:75], v[114:115], 0, v[70:71]
	global_load_lds_dwordx4 v[74:75], off
	s_add_u32 m0, s100, 0x6000
	v_lshl_add_u64 v[74:75], v[116:117], 0, v[70:71]
	global_load_lds_dwordx4 v[74:75], off
	s_add_u32 m0, s100, 0x7000
	v_lshl_add_u64 v[74:75], v[118:119], 0, v[70:71]
	global_load_lds_dwordx4 v[74:75], off
	s_add_u32 m0, s100, 0x0
	v_lshl_add_u64 v[74:75], v[4:5], 0, v[70:71]
	global_load_lds_dwordx4 v[74:75], off
	s_add_u32 m0, s100, 0x1000
	v_lshl_add_u64 v[74:75], v[8:9], 0, v[70:71]
	global_load_lds_dwordx4 v[74:75], off
	s_add_u32 m0, s100, 0x2000
	v_lshl_add_u64 v[74:75], v[12:13], 0, v[70:71]
	global_load_lds_dwordx4 v[74:75], off
	s_add_u32 m0, s100, 0x3000
	v_lshl_add_u64 v[74:75], v[14:15], 0, v[70:71]
	global_load_lds_dwordx4 v[74:75], off
	v_mov_b32_e32 v60, 0
	s_mov_b32 s8, 0
	v_mov_b64_e32 v[120:121], v[106:107]
	s_mov_b32 s44, 0
	v_mov_b32_e32 v61, v60
	v_mov_b32_e32 v62, v60
	v_mov_b32_e32 v63, v60
	v_mov_b32_e32 v56, v60
	v_mov_b32_e32 v57, v60
	v_mov_b32_e32 v58, v60
	v_mov_b32_e32 v59, v60
	v_mov_b32_e32 v52, v60
	v_mov_b32_e32 v53, v60
	v_mov_b32_e32 v54, v60
	v_mov_b32_e32 v55, v60
	v_mov_b32_e32 v48, v60
	v_mov_b32_e32 v49, v60
	v_mov_b32_e32 v50, v60
	v_mov_b32_e32 v51, v60
	v_mov_b32_e32 v44, v60
	v_mov_b32_e32 v45, v60
	v_mov_b32_e32 v46, v60
	v_mov_b32_e32 v47, v60
	v_mov_b32_e32 v40, v60
	v_mov_b32_e32 v41, v60
	v_mov_b32_e32 v42, v60
	v_mov_b32_e32 v43, v60
	v_mov_b32_e32 v36, v60
	v_mov_b32_e32 v37, v60
	v_mov_b32_e32 v38, v60
	v_mov_b32_e32 v39, v60
	v_mov_b32_e32 v32, v60
	v_mov_b32_e32 v33, v60
	v_mov_b32_e32 v34, v60
	v_mov_b32_e32 v35, v60
	v_mov_b32_e32 v28, v60
	v_mov_b32_e32 v29, v60
	v_mov_b32_e32 v30, v60
	v_mov_b32_e32 v31, v60
	v_mov_b32_e32 v24, v60
	v_mov_b32_e32 v25, v60
	v_mov_b32_e32 v26, v60
	v_mov_b32_e32 v27, v60
	v_mov_b32_e32 v20, v60
	v_mov_b32_e32 v21, v60
	v_mov_b32_e32 v22, v60
	v_mov_b32_e32 v23, v60
	v_lshl_add_u64 v[122:123], s[4:5], 0, v[2:3]
	v_lshl_add_u64 v[140:141], s[4:5], 0, v[6:7]
	v_lshl_add_u64 v[142:143], s[4:5], 0, v[10:11]
	v_lshl_add_u64 v[144:145], s[4:5], 0, v[0:1]
	v_mov_b32_e32 v16, v60
	v_mov_b32_e32 v17, v60
	v_mov_b32_e32 v18, v60
	v_mov_b32_e32 v19, v60
	v_mov_b32_e32 v12, v60
	v_mov_b32_e32 v13, v60
	v_mov_b32_e32 v14, v60
	v_mov_b32_e32 v15, v60
	v_mov_b32_e32 v8, v60
	v_mov_b32_e32 v9, v60
	v_mov_b32_e32 v10, v60
	v_mov_b32_e32 v11, v60
	v_mov_b32_e32 v4, v60
	v_mov_b32_e32 v5, v60
	v_mov_b32_e32 v6, v60
	v_mov_b32_e32 v7, v60
	v_mov_b32_e32 v0, v60
	v_mov_b32_e32 v1, v60
	v_mov_b32_e32 v2, v60
	v_mov_b32_e32 v3, v60
	s_waitcnt vmcnt(0)
	s_waitcnt lgkmcnt(0)
	s_barrier
	s_branch .LBB0_1041

; template <bool ABF, bool BBF, class RowF, class ColF, class Epi>
; __device__ __forceinline__ void gemm_tile(char* smem, int K, RowF rowptr, ColF colptr, int ldb, Epi epi) {
;     ...
;   for (int k0 = 0; k0 < K; k0 += BK) {
;     if (k0 + BK < K) gload(k0 + BK);
;     const u16* As = As0 + cur * (GEMM_SMEM / 2);
;     const u16* Bs = As + BM * LDT;
;     {
;       bf16x8 af[2][4], bfr[2][4];
; #pragma unroll
;       for (int ks = 0; ks < 2; ks++) {
; #pragma unroll
;         for (int mi = 0; mi < 4; mi++) af[ks][mi] = *(const bf16x8*)&As[(wm * 64 + mi * 16 + l15) * LDT + (((ks * 4 + kg) ^ swz) << 3)];
; #pragma unroll
;         for (int ni = 0; ni < 4; ni++) bfr[ks][ni] = *(const bf16x8*)&Bs[(wn * 64 + ni * 16 + l15) * LDT + (((ks * 4 + kg) ^ swz) << 3)];
;       }
;       __builtin_amdgcn_sched_barrier(0);
; #pragma unroll
;       for (int ks = 0; ks < 2; ks++)
; #pragma unroll
;         for (int mi = 0; mi < 4; mi++)
; #pragma unroll
;           for (int ni = 0; ni < 4; ni++)
;             acc[mi][ni] = __builtin_amdgcn_mfma_f32_16x16x32_bf16(bfr[ks][ni], af[ks][mi], acc[mi][ni], 0, 0, 0);
;       __builtin_amdgcn_sched_barrier(0);
;     }
;     if (k0 + BK < K) sstore(cur ^ 1);
;     __syncthreads();
;     cur ^= 1;
;   }
.LBB0_1041:
	s_cmpk_lt_u32 s8, 0x3c0
	s_cselect_b64 s[26:27], -1, 0
	s_cmpk_gt_u32 s8, 0x3bf
	s_cselect_b64 s[24:25], -1, 0
	s_and_b64 vcc, exec, s[24:25]
	s_cbranch_vccnz .LBB0_1043
	s_xor_b32 s101, s44, 1
	s_lshl_b32 s101, s101, 15
	s_add_u32 s101, s101, s100
	s_waitcnt vmcnt(1)
	v_lshl_add_u64 v[88:89], v[120:121], 0, v[66:67]
	v_add_co_u32_e32 v84, vcc, 0x10000, v88
	v_lshl_add_u64 v[64:65], v[122:123], 0, v[66:67]
	s_nop 0
	v_addc_co_u32_e32 v85, vcc, 0, v89, vcc
	v_add_co_u32_e32 v90, vcc, 0x20000, v88
	v_lshl_add_u64 v[68:69], v[140:141], 0, v[66:67]
	s_nop 0
	v_addc_co_u32_e32 v91, vcc, 0, v89, vcc
	s_waitcnt vmcnt(0)
	v_add_co_u32_e32 v92, vcc, 0x30000, v88
	v_lshl_add_u64 v[72:73], v[142:143], 0, v[66:67]
	v_lshl_add_u64 v[76:77], v[144:145], 0, v[66:67]
	v_addc_co_u32_e32 v93, vcc, 0, v89, vcc
	s_add_u32 m0, s101, 0x0
	s_nop 0
	global_load_lds_dwordx4 v[64:65], off
	s_nop 0
	s_add_u32 m0, s101, 0x1000
	s_nop 0
	global_load_lds_dwordx4 v[68:69], off
	s_nop 0
	s_add_u32 m0, s101, 0x2000
	s_nop 0
	global_load_lds_dwordx4 v[72:73], off
	s_nop 0
	s_add_u32 m0, s101, 0x3000
	s_nop 0
	global_load_lds_dwordx4 v[76:77], off
	s_nop 0
	s_add_u32 m0, s101, 0x4000
	v_lshl_add_u64 v[88:89], v[88:89], 0, s[2:3]
	global_load_lds_dwordx4 v[88:89], off
	s_nop 0
	s_add_u32 m0, s101, 0x5000
	v_lshl_add_u64 v[84:85], v[84:85], 0, s[2:3]
	global_load_lds_dwordx4 v[84:85], off
	s_nop 0
	s_add_u32 m0, s101, 0x6000
	v_lshl_add_u64 v[90:91], v[90:91], 0, s[2:3]
	global_load_lds_dwordx4 v[90:91], off
	s_nop 0
	s_add_u32 m0, s101, 0x7000
	v_lshl_add_u64 v[92:93], v[92:93], 0, s[2:3]
	global_load_lds_dwordx4 v[92:93], off
.LBB0_1043:
	s_lshl_b32 s45, s44, 15
	s_add_i32 s45, s45, 0
	v_lshlrev_b32_e32 v98, 1, v163
	v_lshlrev_b32_e32 v137, 1, v164
	v_add3_u32 v139, s45, v98, v137
	v_add3_u32 v158, s45, v137, v98
	ds_read_b128 v[146:149], v139
	ds_read_b128 v[150:153], v158 offset:2048
	ds_read_b128 v[154:157], v158 offset:4096
	ds_read_b128 v[172:175], v158 offset:6144
	v_lshlrev_b32_e32 v139, 1, v162
	v_add_u32_e32 v158, s45, v139
	v_add_u32_e32 v98, v158, v98
	ds_read_b128 v[176:179], v98 offset:16384
	ds_read_b128 v[180:183], v98 offset:18432
	ds_read_b128 v[184:187], v98 offset:20480
	ds_read_b128 v[188:191], v98 offset:22528
	v_lshlrev_b32_e32 v98, 1, v165
	v_add_u32_e32 v159, s45, v98
	v_add_u32_e32 v137, v159, v137
	ds_read_b128 v[192:195], v137
	ds_read_b128 v[196:199], v137 offset:2048
	ds_read_b128 v[200:203], v137 offset:4096
	ds_read_b128 v[204:207], v137 offset:6144
	v_add_u32_e32 v137, v159, v139
	v_add_u32_e32 v98, v158, v98
	ds_read_b128 v[208:211], v137 offset:16384
	ds_read_b128 v[212:215], v98 offset:18432
	ds_read_b128 v[216:219], v98 offset:20480
	ds_read_b128 v[220:223], v98 offset:22528
	s_waitcnt lgkmcnt(11)
	v_mfma_f32_16x16x32_bf16 v[60:63], v[176:179], v[146:149], v[60:63]
	s_waitcnt lgkmcnt(10)
	v_mfma_f32_16x16x32_bf16 v[56:59], v[180:183], v[146:149], v[56:59]
	s_waitcnt lgkmcnt(9)
	v_mfma_f32_16x16x32_bf16 v[52:55], v[184:187], v[146:149], v[52:55]
	s_waitcnt lgkmcnt(8)
	v_mfma_f32_16x16x32_bf16 v[48:51], v[188:191], v[146:149], v[48:51]
	v_mfma_f32_16x16x32_bf16 v[44:47], v[176:179], v[150:153], v[44:47]
	v_mfma_f32_16x16x32_bf16 v[40:43], v[180:183], v[150:153], v[40:43]
	v_mfma_f32_16x16x32_bf16 v[36:39], v[184:187], v[150:153], v[36:39]
	v_mfma_f32_16x16x32_bf16 v[32:35], v[188:191], v[150:153], v[32:35]
	v_mfma_f32_16x16x32_bf16 v[28:31], v[176:179], v[154:157], v[28:31]
	v_mfma_f32_16x16x32_bf16 v[24:27], v[180:183], v[154:157], v[24:27]
	v_mfma_f32_16x16x32_bf16 v[20:23], v[184:187], v[154:157], v[20:23]
	v_mfma_f32_16x16x32_bf16 v[16:19], v[188:191], v[154:157], v[16:19]
	v_mfma_f32_16x16x32_bf16 v[12:15], v[176:179], v[172:175], v[12:15]
	v_mfma_f32_16x16x32_bf16 v[8:11], v[180:183], v[172:175], v[8:11]
	v_mfma_f32_16x16x32_bf16 v[4:7], v[184:187], v[172:175], v[4:7]
	v_mfma_f32_16x16x32_bf16 v[0:3], v[188:191], v[172:175], v[0:3]
	s_waitcnt lgkmcnt(3)
	v_mfma_f32_16x16x32_bf16 v[60:63], v[208:211], v[192:195], v[60:63]
	s_waitcnt lgkmcnt(2)
	v_mfma_f32_16x16x32_bf16 v[56:59], v[212:215], v[192:195], v[56:59]
	s_waitcnt lgkmcnt(1)
	v_mfma_f32_16x16x32_bf16 v[52:55], v[216:219], v[192:195], v[52:55]
	s_waitcnt lgkmcnt(0)
	v_mfma_f32_16x16x32_bf16 v[48:51], v[220:223], v[192:195], v[48:51]
	v_mfma_f32_16x16x32_bf16 v[44:47], v[208:211], v[196:199], v[44:47]
	v_mfma_f32_16x16x32_bf16 v[40:43], v[212:215], v[196:199], v[40:43]
	v_mfma_f32_16x16x32_bf16 v[36:39], v[216:219], v[196:199], v[36:39]
	v_mfma_f32_16x16x32_bf16 v[32:35], v[220:223], v[196:199], v[32:35]
	v_mfma_f32_16x16x32_bf16 v[28:31], v[208:211], v[200:203], v[28:31]
	v_mfma_f32_16x16x32_bf16 v[24:27], v[212:215], v[200:203], v[24:27]
	v_mfma_f32_16x16x32_bf16 v[20:23], v[216:219], v[200:203], v[20:23]
	v_mfma_f32_16x16x32_bf16 v[16:19], v[220:223], v[200:203], v[16:19]
	v_mfma_f32_16x16x32_bf16 v[12:15], v[208:211], v[204:207], v[12:15]
	v_mfma_f32_16x16x32_bf16 v[8:11], v[212:215], v[204:207], v[8:11]
	v_mfma_f32_16x16x32_bf16 v[4:7], v[216:219], v[204:207], v[4:7]
	v_mfma_f32_16x16x32_bf16 v[0:3], v[220:223], v[204:207], v[0:3]
	s_andn2_b64 vcc, exec, s[26:27]
	s_cbranch_vccnz .LBB0_1040
	s_waitcnt vmcnt(0)
	s_branch .LBB0_1040

; template <bool ABF, bool BBF, class RowF, class ColF, class Epi>
; __device__ __forceinline__ void gemm_tile(char* smem, int K, RowF rowptr, ColF colptr, int ldb, Epi epi) {
;     ...
; #pragma unroll
;   for (int i = 0; i < 4; i++)
; #pragma unroll
;     for (int j = 0; j < 4; j++) acc[i][j] = f32x4{0.f, 0.f, 0.f, 0.f};
;   constexpr int NA = ABF ? 4 : 8;
;   const int ar0 = ABF ? (tid >> 3) : (tid >> 4);
;   const int ac = ABF ? (tid & 7) * 8 : (tid & 15) * 4;
;   constexpr int ARS = ABF ? 32 : 16;
;   const char* ap[NA];
; #pragma unroll
;   for (int i = 0; i < NA; i++) ap[i] = (const char*)rowptr(ar0 + ARS * i) + ac * (ABF ? 2 : 4);
;   const int bc = tid & 127, kh = tid >> 7;
;   const float* bp = BBF ? nullptr : ((const float*)colptr(bc) + (size_t)(kh * 32) * ldb);
;   const int br0 = tid >> 3, bcc = (tid & 7) * 8;
;   const char* bq[4];
;   if (BBF) {
; #pragma unroll
;     for (int i = 0; i < 4; i++) bq[i] = (const char*)colptr(br0 + 32 * i) + bcc * 2;
;   }
;   u32x4 ra[NA];
;   float rb[BBF ? 1 : 32];
;   u32x4 rbb[BBF ? 4 : 1];
;   auto gload = [&](int k0) {
; #pragma unroll
;     for (int i = 0; i < NA; i++) ra[i] = *(const u32x4*)(ap[i] + (size_t)k0 * (ABF ? 2 : 4));
;     if (BBF) {
; #pragma unroll
;       for (int i = 0; i < 4; i++) rbb[BBF ? i : 0] = *(const u32x4*)(bq[i] + (size_t)k0 * 2);
;     } else {
;       const float* b = bp + (size_t)k0 * ldb;
; #pragma unroll
;       for (int j = 0; j < 32; j++) rb[BBF ? 0 : j] = b[(size_t)j * ldb];
;     }
;   };
; __device__ void phaseE1(const Params& p, char* smem) {
;     ...
;     const int rbg = q, jt = j;
;     int e = 0;
;     while (s_rb[e + 1] <= rbg) e++;
;     const int rb = rbg - s_rb[e];
;     const int cnt = p.cnt[e];
;     const int rows = min(128, cnt - rb * 128);
;     const int* lt = p.list_tok + e * CAP + rb * 128;
;     const int slot0 = s_off[e] + rb * 128;
;     const int j0 = jt * 64;
;     const u16* wg = p.WgT + (size_t)e * DEXP * DM;
;     const u16* wu = p.WuT + (size_t)e * DEXP * DM;
;     auto rowf = [&](int r) { int rr = r < rows ? r : 0; return (const void*)(p.X1B + (size_t)lt[rr] * DM); };
;     auto colf = [&](int c) { return (const void*)(((c & 32) ? wu : wg) + (size_t)(j0 + (c >> 6) * 32 + (c & 31)) * DM); };
.LBB0_1273:
	s_or_b64 exec, exec, s[16:17]
	s_cmp_lg_u32 s33, -1
	s_cselect_b32 s2, s33, 0
	s_cselect_b32 s16, s1, 0
	v_mov_b32_e32 v0, s2
	v_mov_b32_e32 v1, s16
	s_waitcnt lgkmcnt(0)
	s_barrier
	flat_load_dword v0, v[0:1] sc0 sc1
	s_waitcnt vmcnt(0)
	s_mov_b64 s[18:19], -1
	s_waitcnt lgkmcnt(0)
	v_cmp_lt_i32_e32 vcc, v0, v153
	s_and_saveexec_b64 s[16:17], vcc
	s_cbranch_execz .LBB0_1268
	v_lshrrev_b32_e32 v90, 4, v128
	v_xor_b32_e32 v90, v90, v128
	v_and_b32_e32 v90, 7, v90
	v_lshlrev_b32_e32 v92, 4, v90
	v_mov_b32_e32 v93, 0
	v_sub_u32_e32 v94, v92, v124
	v_lshrrev_b32_e32 v90, 6, v128
	v_ashrrev_i32_e32 v95, 31, v94
	v_readfirstlane_b32 s100, v90
	s_lshl_b32 s100, s100, 10
	s_mov_b64 s[18:19], 0
	v_mbcnt_lo_u32_b32 v1, -1, 0
	v_mbcnt_hi_u32_b32 v1, -1, v1
	v_lshl_add_u32 v1, v1, 2, s25
	ds_read_b32 v1, v1
	s_waitcnt lgkmcnt(0)
	v_cmp_le_i32_e32 vcc, v1, v0
	s_bcnt1_i32_b64 s2, vcc
	v_mov_b32_e32 v96, s2
	s_or_b64 exec, exec, s[18:19]
	v_lshl_add_u32 v6, v96, 2, 0
	v_add_u32_e32 v6, 0x10000, v6
	ds_read2_b32 v[6:7], v6 offset1:1
	v_lshl_add_u32 v10, v96, 2, 0
	v_add_u32_e32 v1, 0x10120, v10
	ds_read_b32 v1, v1
	v_lshlrev_b32_e32 v2, 15, v96
	v_mov_b32_e32 v3, v97
	v_lshl_add_u64 v[2:3], v[2:3], 2, s[68:69]
	v_lshlrev_b64 v[4:5], 20, v[96:97]
	s_waitcnt lgkmcnt(0)
	v_sub_u32_e32 v6, v7, v6
	v_sub_u32_e32 v0, v0, v1
	v_lshlrev_b32_e32 v122, 7, v0
	v_ashrrev_i32_e32 v123, 31, v122
	v_lshl_add_u64 v[0:1], v[122:123], 2, v[2:3]
	v_mov_b32_e32 v56, 0
	s_mov_b32 s2, 0
	s_mov_b32 s27, 0
	v_mov_b32_e32 v57, v56
	v_mov_b32_e32 v58, v56
	v_mov_b32_e32 v59, v56
	v_mov_b32_e32 v48, v56
	v_mov_b32_e32 v49, v56
	v_mov_b32_e32 v50, v56
	v_mov_b32_e32 v51, v56
	v_mov_b32_e32 v60, v56
	v_mov_b32_e32 v61, v56
	v_mov_b32_e32 v62, v56
	v_mov_b32_e32 v63, v56
	v_mov_b32_e32 v52, v56
	v_mov_b32_e32 v53, v56
	v_mov_b32_e32 v54, v56
	v_mov_b32_e32 v55, v56
	v_mov_b32_e32 v40, v56
	v_mov_b32_e32 v41, v56
	v_mov_b32_e32 v42, v56
	v_mov_b32_e32 v43, v56
	v_mov_b32_e32 v32, v56
	v_mov_b32_e32 v33, v56
	v_mov_b32_e32 v34, v56
	v_mov_b32_e32 v35, v56
	v_mov_b32_e32 v44, v56
	v_mov_b32_e32 v45, v56
	v_mov_b32_e32 v46, v56
	v_mov_b32_e32 v47, v56
	v_mov_b32_e32 v36, v56
	v_mov_b32_e32 v37, v56
	v_mov_b32_e32 v38, v56
	v_mov_b32_e32 v39, v56
	v_mov_b32_e32 v24, v56
	v_mov_b32_e32 v25, v56
	v_mov_b32_e32 v26, v56
	v_mov_b32_e32 v27, v56
	v_mov_b32_e32 v16, v56
	v_mov_b32_e32 v17, v56
	v_mov_b32_e32 v18, v56
	v_mov_b32_e32 v19, v56
	v_mov_b32_e32 v28, v56
	v_mov_b32_e32 v29, v56
	v_mov_b32_e32 v30, v56
	v_mov_b32_e32 v31, v56
	v_mov_b32_e32 v20, v56
	v_mov_b32_e32 v21, v56
	v_mov_b32_e32 v22, v56
	v_mov_b32_e32 v23, v56
	s_waitcnt vmcnt(0)
	v_sub_u32_e32 v2, v6, v122
	v_min_i32_e32 v123, 0x80, v2
	v_cmp_lt_i32_e32 vcc, v160, v123
	s_nop 1
	v_cndmask_b32_e32 v2, 0, v160, vcc
	v_cmp_lt_i32_e32 vcc, v150, v123
	v_lshlrev_b32_e32 v96, 2, v2
	v_lshl_add_u64 v[2:3], v[0:1], 0, v[96:97]
	v_cndmask_b32_e32 v6, 0, v150, vcc
	v_cmp_lt_i32_e32 vcc, v151, v123
	v_lshlrev_b32_e32 v96, 2, v6
	v_lshl_add_u64 v[6:7], v[0:1], 0, v[96:97]
	v_cndmask_b32_e32 v8, 0, v151, vcc
	v_cmp_lt_i32_e32 vcc, v152, v123
	v_lshlrev_b32_e32 v96, 2, v8
	v_lshl_add_u64 v[8:9], v[0:1], 0, v[96:97]
	v_cndmask_b32_e32 v11, 0, v152, vcc
	v_lshlrev_b32_e32 v96, 2, v11
	global_load_dword v2, v[2:3], off
	v_lshl_add_u64 v[0:1], v[0:1], 0, v[96:97]
	global_load_dword v6, v[6:7], off
	v_add_u32_e32 v96, 0x10000, v10
	global_load_dword v8, v[8:9], off
	v_lshl_add_u64 v[10:11], s[74:75], 0, v[4:5]
	global_load_dword v0, v[0:1], off
	v_lshl_add_u64 v[4:5], s[76:77], 0, v[4:5]
	v_cndmask_b32_e64 v133, v5, v11, s[6:7]
	v_cndmask_b32_e64 v132, v4, v10, s[6:7]
	v_cndmask_b32_e64 v135, v11, v5, s[6:7]
	v_cndmask_b32_e64 v134, v10, v4, s[6:7]
	v_cndmask_b32_e64 v137, v5, v11, s[8:9]
	v_cndmask_b32_e64 v136, v4, v10, s[8:9]
	v_lshl_add_u64 v[4:5], v[132:133], 0, v[112:113]
	v_lshl_add_u64 v[10:11], v[134:135], 0, v[114:115]
	v_lshl_add_u64 v[12:13], v[132:133], 0, v[116:117]
	v_lshl_add_u64 v[14:15], v[136:137], 0, v[118:119]
	v_lshl_add_u64 v[4:5], v[4:5], 0, v[92:93]
	v_lshl_add_u64 v[10:11], v[10:11], 0, v[92:93]
	v_lshl_add_u64 v[12:13], v[12:13], 0, v[92:93]
	v_lshl_add_u64 v[14:15], v[14:15], 0, v[92:93]
	s_add_u32 m0, s100, 0x4000
	s_nop 0
	global_load_lds_dwordx4 v[4:5], off
	s_add_u32 m0, s100, 0x5000
	s_nop 0
	global_load_lds_dwordx4 v[10:11], off
	s_add_u32 m0, s100, 0x6000
	s_nop 0
	global_load_lds_dwordx4 v[12:13], off
	s_add_u32 m0, s100, 0x7000
	s_nop 0
	global_load_lds_dwordx4 v[14:15], off
	v_lshl_add_u64 v[138:139], v[132:133], 0, s[4:5]
	v_lshl_add_u64 v[134:135], v[134:135], 0, v[106:107]
	v_lshl_add_u64 v[176:177], v[136:137], 0, v[110:111]
	v_mov_b32_e32 v10, v56
	v_mov_b32_e32 v11, v56
	v_mov_b32_e32 v12, v56
	v_mov_b32_e32 v13, v56
	v_mov_b32_e32 v14, v56
	v_mov_b32_e32 v15, v56
	v_lshl_add_u64 v[132:133], v[138:139], 0, v[104:105]
	v_lshl_add_u64 v[134:135], v[134:135], 0, s[4:5]
	v_lshl_add_u64 v[136:137], v[138:139], 0, v[108:109]
	v_lshl_add_u64 v[138:139], v[176:177], 0, s[4:5]
	s_waitcnt vmcnt(7)
	v_ashrrev_i32_e32 v3, 31, v2
	v_lshlrev_b64 v[140:141], 11, v[2:3]
	s_waitcnt vmcnt(6)
	v_ashrrev_i32_e32 v7, 31, v6
	v_lshl_add_u64 v[2:3], v[100:101], 0, v[140:141]
	s_waitcnt vmcnt(5)
	v_ashrrev_i32_e32 v9, 31, v8
	v_lshlrev_b64 v[144:145], 11, v[8:9]
	s_waitcnt vmcnt(4)
	v_ashrrev_i32_e32 v1, 31, v0
	v_lshlrev_b64 v[142:143], 11, v[6:7]
	v_lshl_add_u64 v[6:7], v[100:101], 0, v[144:145]
	v_lshlrev_b64 v[146:147], 11, v[0:1]
	v_lshl_add_u64 v[4:5], v[100:101], 0, v[142:143]
	s_add_u32 m0, s100, 0x0
	v_lshl_add_u64 v[90:91], v[2:3], 0, v[94:95]
	global_load_lds_dwordx4 v[90:91], off
	s_add_u32 m0, s100, 0x1000
	v_lshl_add_u64 v[90:91], v[4:5], 0, v[94:95]
	global_load_lds_dwordx4 v[90:91], off
	v_lshl_add_u64 v[0:1], v[100:101], 0, v[146:147]
	s_add_u32 m0, s100, 0x2000
	v_lshl_add_u64 v[90:91], v[6:7], 0, v[94:95]
	global_load_lds_dwordx4 v[90:91], off
	s_add_u32 m0, s100, 0x3000
	v_lshl_add_u64 v[90:91], v[0:1], 0, v[94:95]
	global_load_lds_dwordx4 v[90:91], off
	ds_read_b32 v96, v96
	v_mov_b32_e32 v8, v56
	v_mov_b32_e32 v9, v56
	v_mov_b32_e32 v0, v56
	v_mov_b32_e32 v1, v56
	v_mov_b32_e32 v2, v56
	v_mov_b32_e32 v3, v56
	v_mov_b32_e32 v4, v56
	v_mov_b32_e32 v5, v56
	v_mov_b32_e32 v6, v56
	v_lshl_add_u64 v[140:141], s[10:11], 0, v[140:141]
	v_lshl_add_u64 v[142:143], s[10:11], 0, v[142:143]
	v_lshl_add_u64 v[144:145], s[10:11], 0, v[144:145]
	v_lshl_add_u64 v[146:147], s[10:11], 0, v[146:147]
	v_mov_b32_e32 v7, v56
	s_waitcnt vmcnt(0)
	s_waitcnt lgkmcnt(0)
	s_barrier
	s_branch .LBB0_1278

; template <bool ABF, bool BBF, class RowF, class ColF, class Epi>
; __device__ __forceinline__ void gemm_tile(char* smem, int K, RowF rowptr, ColF colptr, int ldb, Epi epi) {
;     ...
;   for (int k0 = 0; k0 < K; k0 += BK) {
;     if (k0 + BK < K) gload(k0 + BK);
;     const u16* As = As0 + cur * (GEMM_SMEM / 2);
;     const u16* Bs = As + BM * LDT;
;     {
;       bf16x8 af[2][4], bfr[2][4];
; #pragma unroll
;       for (int ks = 0; ks < 2; ks++) {
; #pragma unroll
;         for (int mi = 0; mi < 4; mi++) af[ks][mi] = *(const bf16x8*)&As[(wm * 64 + mi * 16 + l15) * LDT + (((ks * 4 + kg) ^ swz) << 3)];
; #pragma unroll
;         for (int ni = 0; ni < 4; ni++) bfr[ks][ni] = *(const bf16x8*)&Bs[(wn * 64 + ni * 16 + l15) * LDT + (((ks * 4 + kg) ^ swz) << 3)];
;       }
;       __builtin_amdgcn_sched_barrier(0);
; #pragma unroll
;       for (int ks = 0; ks < 2; ks++)
; #pragma unroll
;         for (int mi = 0; mi < 4; mi++)
; #pragma unroll
;           for (int ni = 0; ni < 4; ni++)
;             acc[mi][ni] = __builtin_amdgcn_mfma_f32_16x16x32_bf16(bfr[ks][ni], af[ks][mi], acc[mi][ni], 0, 0, 0);
;       __builtin_amdgcn_sched_barrier(0);
;     }
;     if (k0 + BK < K) sstore(cur ^ 1);
.LBB0_1278:
	s_cmpk_lt_u32 s2, 0x3c0
	s_cselect_b64 s[20:21], -1, 0
	s_cmpk_gt_u32 s2, 0x3bf
	s_cselect_b64 s[18:19], -1, 0
	s_and_b64 vcc, exec, s[18:19]
	s_cbranch_vccnz .LBB0_1280
	s_xor_b32 s101, s27, 1
	s_lshl_b32 s101, s101, 15
	s_add_u32 s101, s101, s100
	s_lshl_b32 s28, s27, 15
	s_add_i32 s28, s28, 0
	v_lshlrev_b32_e32 v176, 1, v163
	v_add_u32_e32 v192, s28, v176
	v_lshlrev_b32_e32 v208, 1, v164
	v_lshl_add_u32 v224, v165, 1, s28
	v_add_u32_e32 v177, v192, v208
	v_add3_u32 v188, s28, v208, v176
	v_add_u32_e32 v204, v192, v175
	v_add_u32_e32 v220, v224, v208
	v_add_u32_e32 v236, v224, v175
	ds_read_b128 v[176:179], v177
	ds_read_b128 v[180:183], v188 offset:2048
	ds_read_b128 v[184:187], v188 offset:4096
	ds_read_b128 v[188:191], v188 offset:6144
	ds_read_b128 v[192:195], v204 offset:16384
	ds_read_b128 v[196:199], v204 offset:18432
	ds_read_b128 v[200:203], v204 offset:20480
	ds_read_b128 v[204:207], v204 offset:22528
	ds_read_b128 v[208:211], v220
	ds_read_b128 v[212:215], v220 offset:2048
	ds_read_b128 v[216:219], v220 offset:4096
	ds_read_b128 v[220:223], v220 offset:6144
	ds_read_b128 v[224:227], v236 offset:16384
	ds_read_b128 v[228:231], v236 offset:18432
	ds_read_b128 v[232:235], v236 offset:20480
	ds_read_b128 v[236:239], v236 offset:22528
	s_waitcnt lgkmcnt(11)
	v_mfma_f32_16x16x32_bf16 v[56:59], v[192:195], v[176:179], v[56:59]
	s_waitcnt lgkmcnt(10)
	v_mfma_f32_16x16x32_bf16 v[48:51], v[196:199], v[176:179], v[48:51]
	s_waitcnt vmcnt(3)
	v_lshl_add_u64 v[64:65], v[140:141], 0, v[92:93]
	s_add_u32 m0, s101, 0x0
	s_nop 0
	global_load_lds_dwordx4 v[64:65], off
	s_waitcnt lgkmcnt(9)
	v_mfma_f32_16x16x32_bf16 v[60:63], v[200:203], v[176:179], v[60:63]
	s_waitcnt lgkmcnt(8)
	v_mfma_f32_16x16x32_bf16 v[52:55], v[204:207], v[176:179], v[52:55]
	v_lshl_add_u64 v[64:65], v[142:143], 0, v[92:93]
	s_add_u32 m0, s101, 0x1000
	s_nop 0
	global_load_lds_dwordx4 v[64:65], off
	v_mfma_f32_16x16x32_bf16 v[40:43], v[192:195], v[180:183], v[40:43]
	v_mfma_f32_16x16x32_bf16 v[32:35], v[196:199], v[180:183], v[32:35]
	v_lshl_add_u64 v[64:65], v[144:145], 0, v[92:93]
	s_add_u32 m0, s101, 0x2000
	s_nop 0
	global_load_lds_dwordx4 v[64:65], off
	v_mfma_f32_16x16x32_bf16 v[44:47], v[200:203], v[180:183], v[44:47]
	v_mfma_f32_16x16x32_bf16 v[36:39], v[204:207], v[180:183], v[36:39]
	v_lshl_add_u64 v[64:65], v[146:147], 0, v[92:93]
	s_add_u32 m0, s101, 0x3000
	s_nop 0
	global_load_lds_dwordx4 v[64:65], off
	v_mfma_f32_16x16x32_bf16 v[24:27], v[192:195], v[184:187], v[24:27]
	v_mfma_f32_16x16x32_bf16 v[16:19], v[196:199], v[184:187], v[16:19]
	v_lshl_add_u64 v[64:65], v[132:133], 0, v[92:93]
	s_waitcnt vmcnt(6)
	v_lshl_add_u64 v[68:69], v[134:135], 0, v[92:93]
	s_waitcnt vmcnt(5)
	v_lshl_add_u64 v[72:73], v[136:137], 0, v[92:93]
	s_waitcnt vmcnt(4)
	v_lshl_add_u64 v[80:81], v[138:139], 0, v[92:93]
	s_add_u32 m0, s101, 0x4000
	s_nop 0
	global_load_lds_dwordx4 v[64:65], off
	v_mfma_f32_16x16x32_bf16 v[28:31], v[200:203], v[184:187], v[28:31]
	v_mfma_f32_16x16x32_bf16 v[20:23], v[204:207], v[184:187], v[20:23]
	s_add_u32 m0, s101, 0x5000
	s_nop 0
	global_load_lds_dwordx4 v[68:69], off
	v_mfma_f32_16x16x32_bf16 v[8:11], v[192:195], v[188:191], v[8:11]
	v_mfma_f32_16x16x32_bf16 v[0:3], v[196:199], v[188:191], v[0:3]
	s_add_u32 m0, s101, 0x6000
	s_nop 0
	global_load_lds_dwordx4 v[72:73], off
	v_mfma_f32_16x16x32_bf16 v[12:15], v[200:203], v[188:191], v[12:15]
	v_mfma_f32_16x16x32_bf16 v[4:7], v[204:207], v[188:191], v[4:7]
	s_add_u32 m0, s101, 0x7000
	s_nop 0
	global_load_lds_dwordx4 v[80:81], off
	s_waitcnt lgkmcnt(3)
	v_mfma_f32_16x16x32_bf16 v[56:59], v[224:227], v[208:211], v[56:59]
	s_waitcnt lgkmcnt(2)
	v_mfma_f32_16x16x32_bf16 v[48:51], v[228:231], v[208:211], v[48:51]
	s_waitcnt lgkmcnt(1)
	v_mfma_f32_16x16x32_bf16 v[60:63], v[232:235], v[208:211], v[60:63]
	s_waitcnt lgkmcnt(0)
	v_mfma_f32_16x16x32_bf16 v[52:55], v[236:239], v[208:211], v[52:55]
	v_mfma_f32_16x16x32_bf16 v[40:43], v[224:227], v[212:215], v[40:43]
	v_mfma_f32_16x16x32_bf16 v[32:35], v[228:231], v[212:215], v[32:35]
	v_mfma_f32_16x16x32_bf16 v[44:47], v[232:235], v[212:215], v[44:47]
	v_mfma_f32_16x16x32_bf16 v[36:39], v[236:239], v[212:215], v[36:39]
	v_mfma_f32_16x16x32_bf16 v[24:27], v[224:227], v[216:219], v[24:27]
	v_mfma_f32_16x16x32_bf16 v[16:19], v[228:231], v[216:219], v[16:19]
	v_mfma_f32_16x16x32_bf16 v[28:31], v[232:235], v[216:219], v[28:31]
	v_mfma_f32_16x16x32_bf16 v[20:23], v[236:239], v[216:219], v[20:23]
	v_mfma_f32_16x16x32_bf16 v[8:11], v[224:227], v[220:223], v[8:11]
	v_mfma_f32_16x16x32_bf16 v[0:3], v[228:231], v[220:223], v[0:3]
	v_mfma_f32_16x16x32_bf16 v[12:15], v[232:235], v[220:223], v[12:15]
	v_mfma_f32_16x16x32_bf16 v[4:7], v[236:239], v[220:223], v[4:7]
	s_branch .Lspr_e1_after

; template <bool ABF, bool BBF, class RowF, class ColF, class Epi>
; __device__ __forceinline__ void gemm_tile(char* smem, int K, RowF rowptr, ColF colptr, int ldb, Epi epi) {
;     ...
;     if (k0 + BK < K) sstore(cur ^ 1);
;     __syncthreads();
;     cur ^= 1;
;   }
.Lspr_e1_after:
	s_andn2_b64 vcc, exec, s[20:21]
	s_cbranch_vccnz .LBB0_1277
	s_waitcnt vmcnt(0)
	s_branch .LBB0_1277

; template <bool ABF, bool BBF, class RowF, class ColF, class Epi>
; __device__ __forceinline__ void gemm_tile(char* smem, int K, RowF rowptr, ColF colptr, int ldb, Epi epi) {
;     ...
;   auto gload = [&](int k0) {
; #pragma unroll
;     for (int i = 0; i < NA; i++) ra[i] = *(const u32x4*)(ap[i] + (size_t)k0 * (ABF ? 2 : 4));
;     if (BBF) {
; #pragma unroll
;       for (int i = 0; i < 4; i++) rbb[BBF ? i : 0] = *(const u32x4*)(bq[i] + (size_t)k0 * 2);
;     } else {
;       const float* b = bp + (size_t)k0 * ldb;
; #pragma unroll
;       for (int j = 0; j < 32; j++) rb[BBF ? 0 : j] = b[(size_t)j * ldb];
; __device__ void phaseE2(const Params& p, char* smem) {
;     ...
;   xcd_queue_run(p.bar + QW_BASE + 1536, s_rb[NEXP], smem + 2 * GEMM_SMEM + 800, [&](int j, int q) {
;     const int rbg = q, nt = j;
;     int e = 0;
;     while (s_rb[e + 1] <= rbg) e++;
;     const int rb = rbg - s_rb[e];
;     const int cnt = p.cnt[e];
;     const int rows = min(128, cnt - rb * 128);
;     const int slot0 = s_off[e] + rb * 128;
;     const int n0 = nt * 128;
;     const float* wd = p.w_down + (size_t)e * DEXP * DM;
;     const float* lg = p.list_gate + e * CAP + rb * 128;
;     auto rowf = [&](int r) { int rr = r < rows ? r : 0; return (const void*)(p.H + (size_t)(slot0 + rr) * DEXP); };
;     auto colf = [&](int c) { return (const void*)(wd + n0 + c); };
.LBB0_1355:
	s_or_b64 exec, exec, s[16:17]
	s_cmp_lg_u32 s33, -1
	s_cselect_b32 s2, s33, 0
	s_cselect_b32 s16, s1, 0
	v_mov_b32_e32 v0, s2
	v_mov_b32_e32 v1, s16
	s_waitcnt lgkmcnt(0)
	s_barrier
	flat_load_dword v2, v[0:1] sc0 sc1
	s_waitcnt vmcnt(0)
	s_mov_b64 s[18:19], -1
	s_waitcnt lgkmcnt(0)
	v_cmp_lt_i32_e32 vcc, v2, v108
	s_and_saveexec_b64 s[16:17], vcc
	s_cbranch_execz .LBB0_1350
	s_mov_b64 s[18:19], 0
	v_mbcnt_lo_u32_b32 v3, -1, 0
	v_mbcnt_hi_u32_b32 v3, -1, v3
	v_lshl_add_u32 v3, v3, 2, s24
	ds_read_b32 v3, v3
	s_waitcnt lgkmcnt(0)
	v_cmp_le_i32_e32 vcc, v3, v2
	s_bcnt1_i32_b64 s2, vcc
	v_mov_b32_e32 v80, s2
	s_lshl_b32 s20, s2, 21
	s_mov_b32 s21, 0
	v_lshl_add_u64 v[96:97], v[90:91], 0, s[20:21]
	s_or_b64 exec, exec, s[18:19]
	v_mul_u32_u24_e32 v0, 0x20100, v80
	v_mov_b32_e32 v1, 0
	v_lshl_add_u64 v[0:1], v[0:1], 0, s[62:63]
	global_load_dword v3, v[0:1], off
	v_lshl_add_u32 v4, v80, 2, 0
	v_lshlrev_b64 v[0:1], 21, v[80:81]
	v_add_u32_e32 v5, 0x10120, v4
	v_add_u32_e32 v4, 0x10000, v4
	v_lshl_add_u64 v[0:1], v[92:93], 0, v[0:1]
	ds_read_b32 v22, v5
	ds_read_b32 v23, v4
	v_add_co_u32_e32 v4, vcc, s26, v0
	v_mov_b32_e32 v64, 0
	s_nop 0
	v_addc_co_u32_e32 v5, vcc, 0, v1, vcc
	v_add_co_u32_e32 v6, vcc, s27, v0
	s_waitcnt lgkmcnt(1)
	v_sub_u32_e32 v2, v2, v22
	v_addc_co_u32_e32 v7, vcc, 0, v1, vcc
	v_add_co_u32_e32 v8, vcc, s28, v0
	v_lshlrev_b32_e32 v98, 7, v2
	s_nop 0
	v_addc_co_u32_e32 v9, vcc, 0, v1, vcc
	v_add_co_u32_e32 v10, vcc, s29, v0
	s_waitcnt lgkmcnt(0)
	v_add_u32_e32 v117, v23, v98
	v_addc_co_u32_e32 v11, vcc, 0, v1, vcc
	v_add_co_u32_e32 v12, vcc, s30, v0
	s_mov_b32 s2, 0
	s_nop 0
	v_addc_co_u32_e32 v13, vcc, 0, v1, vcc
	v_add_co_u32_e32 v14, vcc, s31, v0
	s_mov_b32 s47, 0
	s_nop 0
	v_addc_co_u32_e32 v15, vcc, 0, v1, vcc
	v_add_co_u32_e32 v16, vcc, s36, v0
	v_mov_b32_e32 v65, v64
	s_nop 0
	v_addc_co_u32_e32 v17, vcc, 0, v1, vcc
	v_add_co_u32_e32 v18, vcc, s25, v0
	global_load_dword v141, v[0:1], off
	global_load_dword v99, v[4:5], off offset:-4096
	global_load_dword v119, v[4:5], off
	global_load_dword v120, v[6:7], off offset:-4096
	global_load_dword v121, v[6:7], off
	global_load_dword v122, v[8:9], off offset:-4096
	global_load_dword v123, v[8:9], off
	global_load_dword v128, v[10:11], off offset:-4096
	global_load_dword v130, v[10:11], off
	global_load_dword v132, v[12:13], off offset:-4096
	global_load_dword v133, v[12:13], off
	global_load_dword v134, v[14:15], off offset:-4096
	global_load_dword v135, v[14:15], off
	global_load_dword v136, v[16:17], off offset:-4096
	global_load_dword v137, v[16:17], off
	v_addc_co_u32_e32 v19, vcc, 0, v1, vcc
	v_add_co_u32_e32 v20, vcc, s37, v0
	v_mov_b32_e32 v66, v64
	s_nop 0
	v_addc_co_u32_e32 v21, vcc, 0, v1, vcc
	v_mov_b32_e32 v67, v64
	v_mov_b32_e32 v76, v64
	v_mov_b32_e32 v77, v64
	v_mov_b32_e32 v78, v64
	v_mov_b32_e32 v79, v64
	v_mov_b32_e32 v72, v64
	v_mov_b32_e32 v73, v64
	v_mov_b32_e32 v74, v64
	v_mov_b32_e32 v75, v64
	v_mov_b32_e32 v68, v64
	v_mov_b32_e32 v69, v64
	v_mov_b32_e32 v70, v64
	v_mov_b32_e32 v71, v64
	v_mov_b32_e32 v60, v64
	v_mov_b32_e32 v61, v64
	v_mov_b32_e32 v62, v64
	v_mov_b32_e32 v63, v64
	v_mov_b32_e32 v56, v64
	v_mov_b32_e32 v57, v64
	v_mov_b32_e32 v58, v64
	v_mov_b32_e32 v59, v64
	v_mov_b32_e32 v52, v64
	v_mov_b32_e32 v53, v64
	v_mov_b32_e32 v54, v64
	v_mov_b32_e32 v55, v64
	v_mov_b32_e32 v48, v64
	v_mov_b32_e32 v49, v64
	v_mov_b32_e32 v50, v64
	s_waitcnt vmcnt(15)
; template <bool ABF, bool BBF, class RowF, class ColF, class Epi>
; __device__ __forceinline__ void gemm_tile(char* smem, int K, RowF rowptr, ColF colptr, int ldb, Epi epi) {
;     ...
;   auto gload = [&](int k0) {
; #pragma unroll
;     for (int i = 0; i < NA; i++) ra[i] = *(const u32x4*)(ap[i] + (size_t)k0 * (ABF ? 2 : 4));
;     if (BBF) {
; #pragma unroll
;       for (int i = 0; i < 4; i++) rbb[BBF ? i : 0] = *(const u32x4*)(bq[i] + (size_t)k0 * 2);
;     } else {
;       const float* b = bp + (size_t)k0 * ldb;
; #pragma unroll
;       for (int j = 0; j < 32; j++) rb[BBF ? 0 : j] = b[(size_t)j * ldb];
;     }
;   };
;   auto sstore = [&](int buf) {
;     u16* As = As0 + buf * (GEMM_SMEM / 2);
;     u16* Bs = As + BM * LDT;
; #pragma unroll
;     for (int i = 0; i < NA; i++) {
;       if (ABF) {
;         { const int row = ar0 + ARS * i; *(u32x4*)&As[row * LDT + (((ac >> 3) ^ ((row >> 1) & 7)) << 3)] = ra[i]; }
;       } else {
;         u32x2 v;
;         v[0] = pack2(__uint_as_float(ra[i][0]), __uint_as_float(ra[i][1]));
;         v[1] = pack2(__uint_as_float(ra[i][2]), __uint_as_float(ra[i][3]));
;         { const int row = ar0 + ARS * i; *(u32x2*)&As[row * LDT + (((ac >> 3) ^ ((row >> 1) & 7)) << 3) + (ac & 4)] = v; }
;       }
;     }
;     if (BBF) {
; #pragma unroll
;       for (int i = 0; i < 4; i++) { const int row = br0 + 32 * i; *(u32x4*)&Bs[row * LDT + (((bcc >> 3) ^ ((row >> 1) & 7)) << 3)] = rbb[BBF ? i : 0]; }
;     } else {
; #pragma unroll
;       for (int j = 0; j < 4; j++) {
;         u32x4 v;
;         v[0] = pack2(rb[BBF ? 0 : 8 * j + 0], rb[BBF ? 0 : 8 * j + 1]);
;         v[1] = pack2(rb[BBF ? 0 : 8 * j + 2], rb[BBF ? 0 : 8 * j + 3]);
;         v[2] = pack2(rb[BBF ? 0 : 8 * j + 4], rb[BBF ? 0 : 8 * j + 5]);
;         v[3] = pack2(rb[BBF ? 0 : 8 * j + 6], rb[BBF ? 0 : 8 * j + 7]);
;         *(u32x4*)&Bs[bc * LDT + (((kh * 4 + j) ^ ((bc >> 1) & 7)) << 3)] = v;
;       }
;     }
;   };
;   gload(0);
;   sstore(0);
	v_sub_u32_e32 v2, v3, v98
	v_min_i32_e32 v118, 0x80, v2
	v_cmp_lt_i32_e32 vcc, v160, v118
	v_mov_b32_e32 v51, v64
	v_mov_b32_e32 v28, v64
	v_cndmask_b32_e32 v2, 0, v160, vcc
	v_cmp_lt_i32_e32 vcc, v150, v118
	v_add_u32_e32 v2, v2, v117
	v_mov_b32_e32 v29, v64
	v_cndmask_b32_e32 v3, 0, v150, vcc
	v_cmp_lt_i32_e32 vcc, v151, v118
	v_add_u32_e32 v4, v3, v117
	v_ashrrev_i32_e32 v3, 31, v2
	v_cndmask_b32_e32 v5, 0, v151, vcc
	v_cmp_lt_i32_e32 vcc, v152, v118
	v_add_u32_e32 v6, v5, v117
	v_ashrrev_i32_e32 v5, 31, v4
	v_cndmask_b32_e32 v7, 0, v152, vcc
	v_add_co_u32_e32 v10, vcc, s38, v0
	v_add_u32_e32 v8, v7, v117
	s_nop 0
	v_addc_co_u32_e32 v11, vcc, 0, v1, vcc
	v_add_co_u32_e32 v12, vcc, s39, v0
	v_ashrrev_i32_e32 v7, 31, v6
	s_nop 0
	v_addc_co_u32_e32 v13, vcc, 0, v1, vcc
	global_load_dword v138, v[18:19], off offset:-4096
	global_load_dword v139, v[18:19], off
	global_load_dword v140, v[20:21], off offset:-4096
	global_load_dword v142, v[20:21], off
	global_load_dword v143, v[10:11], off offset:-4096
	global_load_dword v144, v[10:11], off
	global_load_dword v145, v[12:13], off offset:-4096
	global_load_dword v146, v[12:13], off
	v_add_co_u32_e32 v10, vcc, s40, v0
	v_lshlrev_b64 v[16:17], 10, v[2:3]
	s_nop 0
	v_addc_co_u32_e32 v11, vcc, 0, v1, vcc
	v_add_co_u32_e32 v12, vcc, s41, v0
	v_ashrrev_i32_e32 v9, 31, v8
	s_nop 0
	v_addc_co_u32_e32 v13, vcc, 0, v1, vcc
	v_add_co_u32_e32 v14, vcc, s42, v0
	v_lshlrev_b64 v[22:23], 10, v[4:5]
	s_nop 0
	v_addc_co_u32_e32 v15, vcc, 0, v1, vcc
	v_add_co_u32_e32 v18, vcc, s43, v0
	v_lshlrev_b64 v[24:25], 10, v[6:7]
	s_nop 0
	v_addc_co_u32_e32 v19, vcc, 0, v1, vcc
	v_add_co_u32_e32 v0, vcc, s44, v0
	v_lshl_add_u64 v[2:3], v[86:87], 0, v[16:17]
	s_nop 0
	v_addc_co_u32_e32 v1, vcc, 0, v1, vcc
	global_load_dword v147, v[10:11], off offset:-4096
	global_load_dword v153, v[10:11], off
	global_load_dword v154, v[12:13], off offset:-4096
	global_load_dword v155, v[12:13], off
	global_load_dword v156, v[14:15], off offset:-4096
	global_load_dword v157, v[14:15], off
	global_load_dword v158, v[18:19], off offset:-4096
	global_load_dword v159, v[18:19], off
	global_load_dword v170, v[0:1], off
	v_lshlrev_b64 v[18:19], 10, v[8:9]
	v_lshl_add_u64 v[4:5], v[86:87], 0, v[22:23]
	v_lshl_add_u64 v[6:7], v[86:87], 0, v[24:25]
	v_lshl_add_u64 v[0:1], v[86:87], 0, v[18:19]
	v_lshrrev_b32_e32 v46, 2, v149
	v_lshrrev_b32_e32 v35, 4, v46
	v_xor_b32_e32 v35, v35, v46
	v_and_b32_e32 v35, 7, v35
	v_lshlrev_b32_e32 v34, 4, v35
	v_mov_b32_e32 v35, 0
	v_sub_u32_e32 v38, v34, v124
	v_lshrrev_b32_e32 v46, 6, v46
	v_ashrrev_i32_e32 v39, 31, v38
	v_readfirstlane_b32 s100, v46
	s_lshl_b32 s100, s100, 10
	s_add_u32 m0, s100, 0x0
	v_lshl_add_u64 v[42:43], v[2:3], 0, v[38:39]
	global_load_lds_dwordx4 v[42:43], off
	s_add_u32 m0, s100, 0x1000
	v_lshl_add_u64 v[42:43], v[4:5], 0, v[38:39]
	global_load_lds_dwordx4 v[42:43], off
	s_add_u32 m0, s100, 0x2000
	v_lshl_add_u64 v[42:43], v[6:7], 0, v[38:39]
	global_load_lds_dwordx4 v[42:43], off
	s_add_u32 m0, s100, 0x3000
	v_lshl_add_u64 v[42:43], v[0:1], 0, v[38:39]
	global_load_lds_dwordx4 v[42:43], off
	s_waitcnt vmcnt(34)
	v_cvt_pk_bf16_f32 v0, v141, v99
	s_waitcnt vmcnt(32)
	v_cvt_pk_bf16_f32 v1, v119, v120
	s_waitcnt vmcnt(30)
	v_cvt_pk_bf16_f32 v2, v121, v122
	s_waitcnt vmcnt(28)
	v_cvt_pk_bf16_f32 v3, v123, v128
	s_waitcnt vmcnt(26)
	v_cvt_pk_bf16_f32 v4, v130, v132
	s_waitcnt vmcnt(24)
	v_cvt_pk_bf16_f32 v5, v133, v134
	s_waitcnt vmcnt(22)
	v_cvt_pk_bf16_f32 v6, v135, v136
	v_lshl_add_u64 v[100:101], s[8:9], 0, v[16:17]
	v_lshl_add_u64 v[102:103], s[8:9], 0, v[22:23]
	v_lshl_add_u64 v[104:105], s[8:9], 0, v[24:25]
	v_lshl_add_u64 v[106:107], s[8:9], 0, v[18:19]
	v_mov_b32_e32 v30, v64
	v_mov_b32_e32 v31, v64
	v_mov_b32_e32 v24, v64
	v_mov_b32_e32 v25, v64
	v_mov_b32_e32 v26, v64
	v_mov_b32_e32 v27, v64
	v_mov_b32_e32 v20, v64
	v_mov_b32_e32 v21, v64
	v_mov_b32_e32 v22, v64
	v_mov_b32_e32 v23, v64
	v_mov_b32_e32 v16, v64
	v_mov_b32_e32 v17, v64
	v_mov_b32_e32 v18, v64
	v_mov_b32_e32 v19, v64
	s_waitcnt vmcnt(20)
	v_cvt_pk_bf16_f32 v7, v137, v138
	s_waitcnt vmcnt(18)
	v_cvt_pk_bf16_f32 v8, v139, v140
	s_waitcnt vmcnt(16)
	v_cvt_pk_bf16_f32 v9, v142, v143
	s_waitcnt vmcnt(14)
	v_cvt_pk_bf16_f32 v10, v144, v145
	s_waitcnt vmcnt(12)
	v_cvt_pk_bf16_f32 v11, v146, v147
	s_waitcnt vmcnt(10)
	v_cvt_pk_bf16_f32 v12, v153, v154
	s_waitcnt vmcnt(8)
	v_cvt_pk_bf16_f32 v13, v155, v156
	s_waitcnt vmcnt(6)
	v_cvt_pk_bf16_f32 v14, v157, v158
	s_waitcnt vmcnt(4)
	v_cvt_pk_bf16_f32 v15, v159, v170
	s_waitcnt vmcnt(3)
	s_waitcnt vmcnt(2)
	s_waitcnt vmcnt(1)
	s_waitcnt vmcnt(0)
	ds_write_b128 v113, v[0:3] offset:16384
	ds_write_b128 v114, v[4:7] offset:16384
	ds_write_b128 v115, v[8:11] offset:16384
	ds_write_b128 v116, v[12:15] offset:16384
	v_mov_b32_e32 v12, v64
	v_mov_b32_e32 v13, v64
	v_mov_b32_e32 v14, v64
	v_mov_b32_e32 v15, v64
	v_mov_b32_e32 v8, v64
	v_mov_b32_e32 v9, v64
	v_mov_b32_e32 v10, v64
	v_mov_b32_e32 v11, v64
	v_mov_b32_e32 v4, v64
	v_mov_b32_e32 v5, v64
	v_mov_b32_e32 v6, v64
	v_mov_b32_e32 v7, v64
	v_mov_b32_e32 v0, v64
	v_mov_b32_e32 v1, v64
	v_mov_b32_e32 v2, v64
	v_mov_b32_e32 v3, v64
	s_waitcnt lgkmcnt(0)
	s_barrier
	s_branch .LBB0_1360

; template <bool ABF, bool BBF, class RowF, class ColF, class Epi>
; __device__ __forceinline__ void gemm_tile(char* smem, int K, RowF rowptr, ColF colptr, int ldb, Epi epi) {
;     ...
;   auto gload = [&](int k0) {
; #pragma unroll
;     for (int i = 0; i < NA; i++) ra[i] = *(const u32x4*)(ap[i] + (size_t)k0 * (ABF ? 2 : 4));
;     if (BBF) {
; #pragma unroll
;       for (int i = 0; i < 4; i++) rbb[BBF ? i : 0] = *(const u32x4*)(bq[i] + (size_t)k0 * 2);
;     } else {
;       const float* b = bp + (size_t)k0 * ldb;
; #pragma unroll
;       for (int j = 0; j < 32; j++) rb[BBF ? 0 : j] = b[(size_t)j * ldb];
;     }
;   };
;     ...
;   for (int k0 = 0; k0 < K; k0 += BK) {
;     if (k0 + BK < K) gload(k0 + BK);
.LBB0_1360:
	s_cmpk_lt_u32 s2, 0x1c0
	s_cselect_b64 s[20:21], -1, 0
	s_cmpk_gt_u32 s2, 0x1bf
	s_cselect_b64 s[18:19], -1, 0
	s_and_b64 vcc, exec, s[18:19]
	s_cbranch_vccnz .LBB0_1362
	s_xor_b32 s101, s47, 1
	s_lshl_b32 s101, s101, 15
	s_add_u32 s101, s101, s100
	s_waitcnt vmcnt(29)
	v_add_co_u32_e32 v120, vcc, 0x1000, v96
	v_lshl_add_u64 v[32:33], v[100:101], 0, v[34:35]
	s_waitcnt vmcnt(28)
	v_addc_co_u32_e32 v121, vcc, 0, v97, vcc
	s_waitcnt vmcnt(27)
	v_add_co_u32_e32 v122, vcc, 0x2000, v96
	v_lshl_add_u64 v[36:37], v[102:103], 0, v[34:35]
	s_waitcnt vmcnt(26)
	v_addc_co_u32_e32 v123, vcc, 0, v97, vcc
	s_waitcnt vmcnt(23)
	v_add_co_u32_e32 v132, vcc, 0x3000, v96
	v_lshl_add_u64 v[40:41], v[104:105], 0, v[34:35]
	s_waitcnt vmcnt(22)
	v_addc_co_u32_e32 v133, vcc, 0, v97, vcc
	s_waitcnt vmcnt(21)
	v_add_co_u32_e32 v134, vcc, 0x4000, v96
	v_lshl_add_u64 v[44:45], v[106:107], 0, v[34:35]
	s_waitcnt vmcnt(20)
	v_addc_co_u32_e32 v135, vcc, 0, v97, vcc
	s_waitcnt vmcnt(19)
	v_add_co_u32_e32 v136, vcc, 0x5000, v96
	s_add_u32 m0, s101, 0x0
	s_nop 0
	global_load_lds_dwordx4 v[32:33], off
	s_waitcnt vmcnt(19)
	v_addc_co_u32_e32 v137, vcc, 0, v97, vcc
	s_waitcnt vmcnt(18)
	v_add_co_u32_e32 v138, vcc, 0x6000, v96
	s_add_u32 m0, s101, 0x1000
	s_nop 0
	global_load_lds_dwordx4 v[36:37], off
	s_waitcnt vmcnt(18)
	v_addc_co_u32_e32 v139, vcc, 0, v97, vcc
	s_waitcnt vmcnt(17)
	v_add_co_u32_e32 v140, vcc, 0x7000, v96
	s_add_u32 m0, s101, 0x2000
	s_nop 0
	global_load_lds_dwordx4 v[40:41], off
	s_waitcnt vmcnt(10)
	v_addc_co_u32_e32 v141, vcc, 0, v97, vcc
	v_add_co_u32_e32 v142, vcc, 0x8000, v96
	s_add_u32 m0, s101, 0x3000
	s_nop 0
	global_load_lds_dwordx4 v[44:45], off
	s_nop 0
	v_addc_co_u32_e32 v143, vcc, 0, v97, vcc
	global_load_dword v99, v[120:121], off
	global_load_dword v119, v[122:123], off
	s_nop 0
	global_load_dword v120, v[132:133], off
	global_load_dword v121, v[134:135], off
	global_load_dword v122, v[136:137], off
	global_load_dword v123, v[138:139], off
	global_load_dword v128, v[140:141], off
	global_load_dword v130, v[142:143], off
	v_add_co_u32_e32 v132, vcc, 0x9000, v96
	s_nop 1
	v_addc_co_u32_e32 v133, vcc, 0, v97, vcc
	v_add_co_u32_e32 v134, vcc, 0xa000, v96
	s_nop 1
	v_addc_co_u32_e32 v135, vcc, 0, v97, vcc
	v_add_co_u32_e32 v136, vcc, 0xb000, v96
	s_nop 1
	v_addc_co_u32_e32 v137, vcc, 0, v97, vcc
	v_add_co_u32_e32 v138, vcc, 0xc000, v96
	s_nop 1
	v_addc_co_u32_e32 v139, vcc, 0, v97, vcc
	v_add_co_u32_e32 v140, vcc, 0xd000, v96
	s_nop 1
	v_addc_co_u32_e32 v141, vcc, 0, v97, vcc
	v_add_co_u32_e32 v142, vcc, 0xe000, v96
	s_nop 1
	v_addc_co_u32_e32 v143, vcc, 0, v97, vcc
	v_add_co_u32_e32 v144, vcc, 0xf000, v96
	s_nop 1
	v_addc_co_u32_e32 v145, vcc, 0, v97, vcc
	v_add_co_u32_e32 v146, vcc, s25, v96
	s_nop 1
	v_addc_co_u32_e32 v147, vcc, 0, v97, vcc
	global_load_dword v132, v[132:133], off
	s_nop 0
	global_load_dword v133, v[134:135], off
	s_nop 0
	global_load_dword v134, v[136:137], off
	global_load_dword v135, v[138:139], off
	s_nop 0
	global_load_dword v136, v[140:141], off
	global_load_dword v137, v[142:143], off
	global_load_dword v138, v[144:145], off
	global_load_dword v139, v[146:147], off
	v_add_co_u32_e32 v140, vcc, 0x11000, v96
	s_nop 1
	v_addc_co_u32_e32 v141, vcc, 0, v97, vcc
	v_add_co_u32_e32 v142, vcc, 0x12000, v96
	s_nop 1
	v_addc_co_u32_e32 v143, vcc, 0, v97, vcc
	v_add_co_u32_e32 v144, vcc, 0x13000, v96
	s_nop 1
	v_addc_co_u32_e32 v145, vcc, 0, v97, vcc
	v_add_co_u32_e32 v146, vcc, 0x14000, v96
	s_nop 1
	v_addc_co_u32_e32 v147, vcc, 0, v97, vcc
	s_waitcnt vmcnt(26)
	v_add_co_u32_e32 v154, vcc, 0x15000, v96
	s_waitcnt vmcnt(25)
	s_nop 0
	v_addc_co_u32_e32 v155, vcc, 0, v97, vcc
	s_waitcnt vmcnt(24)
	v_add_co_u32_e32 v156, vcc, 0x16000, v96
	s_waitcnt vmcnt(23)
	s_nop 0
	v_addc_co_u32_e32 v157, vcc, 0, v97, vcc
	s_waitcnt vmcnt(22)
	v_add_co_u32_e32 v158, vcc, 0x17000, v96
	s_waitcnt vmcnt(21)
	s_nop 0
	v_addc_co_u32_e32 v159, vcc, 0, v97, vcc
	s_waitcnt vmcnt(20)
	v_add_co_u32_e32 v170, vcc, 0x18000, v96
	s_nop 1
	v_addc_co_u32_e32 v171, vcc, 0, v97, vcc
	global_load_dword v140, v[140:141], off
	s_nop 0
	global_load_dword v142, v[142:143], off
	s_nop 0
	global_load_dword v143, v[144:145], off
	s_nop 0
	global_load_dword v144, v[146:147], off
	global_load_dword v145, v[154:155], off
	s_nop 0
	global_load_dword v146, v[156:157], off
	global_load_dword v147, v[158:159], off
	global_load_dword v153, v[170:171], off
	v_add_co_u32_e32 v154, vcc, 0x19000, v96
	s_nop 1
	v_addc_co_u32_e32 v155, vcc, 0, v97, vcc
	v_add_co_u32_e32 v156, vcc, 0x1a000, v96
	s_nop 1
	v_addc_co_u32_e32 v157, vcc, 0, v97, vcc
	v_add_co_u32_e32 v158, vcc, 0x1b000, v96
	s_nop 1
	v_addc_co_u32_e32 v159, vcc, 0, v97, vcc
	v_add_co_u32_e32 v170, vcc, 0x1c000, v96
	s_nop 1
	v_addc_co_u32_e32 v171, vcc, 0, v97, vcc
	v_add_co_u32_e32 v172, vcc, 0x1d000, v96
	s_nop 1
	v_addc_co_u32_e32 v173, vcc, 0, v97, vcc
	v_add_co_u32_e32 v174, vcc, 0x1e000, v96
	s_nop 1
	v_addc_co_u32_e32 v175, vcc, 0, v97, vcc
	v_add_co_u32_e32 v176, vcc, 0x1f000, v96
	s_nop 1
	v_addc_co_u32_e32 v177, vcc, 0, v97, vcc
	global_load_dword v141, v[96:97], off
	s_nop 0
	global_load_dword v154, v[154:155], off
	s_nop 0
	global_load_dword v155, v[156:157], off
	s_nop 0
	global_load_dword v156, v[158:159], off
	global_load_dword v157, v[170:171], off
	s_nop 0
	global_load_dword v158, v[172:173], off
	global_load_dword v159, v[174:175], off
	global_load_dword v170, v[176:177], off
; template <bool ABF, bool BBF, class RowF, class ColF, class Epi>
; __device__ __forceinline__ void gemm_tile(char* smem, int K, RowF rowptr, ColF colptr, int ldb, Epi epi) {
;     ...
;     if (BBF) {
; #pragma unroll
;       for (int i = 0; i < 4; i++) { const int row = br0 + 32 * i; *(u32x4*)&Bs[row * LDT + (((bcc >> 3) ^ ((row >> 1) & 7)) << 3)] = rbb[BBF ? i : 0]; }
;     } else {
; #pragma unroll
;       for (int j = 0; j < 4; j++) {
;         u32x4 v;
;         v[0] = pack2(rb[BBF ? 0 : 8 * j + 0], rb[BBF ? 0 : 8 * j + 1]);
;         v[1] = pack2(rb[BBF ? 0 : 8 * j + 2], rb[BBF ? 0 : 8 * j + 3]);
;         v[2] = pack2(rb[BBF ? 0 : 8 * j + 4], rb[BBF ? 0 : 8 * j + 5]);
;         v[3] = pack2(rb[BBF ? 0 : 8 * j + 6], rb[BBF ? 0 : 8 * j + 7]);
;         *(u32x4*)&Bs[bc * LDT + (((kh * 4 + j) ^ ((bc >> 1) & 7)) << 3)] = v;
;       }
;     }
;     ...
;     {
;       bf16x8 af[2][4], bfr[2][4];
; #pragma unroll
;       for (int ks = 0; ks < 2; ks++) {
; #pragma unroll
;         for (int mi = 0; mi < 4; mi++) af[ks][mi] = *(const bf16x8*)&As[(wm * 64 + mi * 16 + l15) * LDT + (((ks * 4 + kg) ^ swz) << 3)];
; #pragma unroll
;         for (int ni = 0; ni < 4; ni++) bfr[ks][ni] = *(const bf16x8*)&Bs[(wn * 64 + ni * 16 + l15) * LDT + (((ks * 4 + kg) ^ swz) << 3)];
;       }
;       __builtin_amdgcn_sched_barrier(0);
; #pragma unroll
;       for (int ks = 0; ks < 2; ks++)
; #pragma unroll
;         for (int mi = 0; mi < 4; mi++)
; #pragma unroll
;           for (int ni = 0; ni < 4; ni++)
;             acc[mi][ni] = __builtin_amdgcn_mfma_f32_16x16x32_bf16(bfr[ks][ni], af[ks][mi], acc[mi][ni], 0, 0, 0);
;       __builtin_amdgcn_sched_barrier(0);
;     }
;     if (k0 + BK < K) sstore(cur ^ 1);
.LBB0_1362:
	s_lshl_b32 s48, s47, 15
	s_add_i32 s48, s48, 0
	v_lshlrev_b32_e32 v220, 1, v162
	v_lshlrev_b32_e32 v171, 1, v163
	v_lshlrev_b32_e32 v204, 1, v164
	v_add_u32_e32 v221, s48, v220
	v_add3_u32 v172, s48, v171, v204
	v_add3_u32 v184, s48, v204, v171
	v_add_u32_e32 v171, v221, v171
	ds_read_b128 v[172:175], v172
	ds_read_b128 v[176:179], v184 offset:2048
	ds_read_b128 v[180:183], v184 offset:4096
	ds_read_b128 v[184:187], v184 offset:6144
	ds_read_b128 v[188:191], v171 offset:16384
	ds_read_b128 v[192:195], v171 offset:18432
	ds_read_b128 v[196:199], v171 offset:20480
	ds_read_b128 v[200:203], v171 offset:22528
	v_lshlrev_b32_e32 v171, 1, v165
	v_add_u32_e32 v222, s48, v171
	v_add_u32_e32 v216, v222, v204
	v_add_u32_e32 v220, v222, v220
	ds_read_b128 v[204:207], v216
	ds_read_b128 v[208:211], v216 offset:2048
	ds_read_b128 v[212:215], v216 offset:4096
	ds_read_b128 v[216:219], v216 offset:6144
	v_add_u32_e32 v171, v221, v171
	ds_read_b128 v[220:223], v220 offset:16384
	ds_read_b128 v[224:227], v171 offset:18432
	ds_read_b128 v[228:231], v171 offset:20480
	ds_read_b128 v[232:235], v171 offset:22528
	s_waitcnt lgkmcnt(11)
	v_mfma_f32_16x16x32_bf16 v[64:67], v[188:191], v[172:175], v[64:67]
	s_waitcnt lgkmcnt(10)
	v_mfma_f32_16x16x32_bf16 v[76:79], v[192:195], v[172:175], v[76:79]
	s_waitcnt lgkmcnt(9)
	v_mfma_f32_16x16x32_bf16 v[72:75], v[196:199], v[172:175], v[72:75]
	s_waitcnt lgkmcnt(8)
	v_mfma_f32_16x16x32_bf16 v[68:71], v[200:203], v[172:175], v[68:71]
	v_mfma_f32_16x16x32_bf16 v[60:63], v[188:191], v[176:179], v[60:63]
	v_mfma_f32_16x16x32_bf16 v[56:59], v[192:195], v[176:179], v[56:59]
	v_mfma_f32_16x16x32_bf16 v[52:55], v[196:199], v[176:179], v[52:55]
	v_mfma_f32_16x16x32_bf16 v[48:51], v[200:203], v[176:179], v[48:51]
	v_mfma_f32_16x16x32_bf16 v[28:31], v[188:191], v[180:183], v[28:31]
	v_mfma_f32_16x16x32_bf16 v[24:27], v[192:195], v[180:183], v[24:27]
	v_mfma_f32_16x16x32_bf16 v[20:23], v[196:199], v[180:183], v[20:23]
	v_mfma_f32_16x16x32_bf16 v[16:19], v[200:203], v[180:183], v[16:19]
	v_mfma_f32_16x16x32_bf16 v[12:15], v[188:191], v[184:187], v[12:15]
	v_mfma_f32_16x16x32_bf16 v[8:11], v[192:195], v[184:187], v[8:11]
	v_mfma_f32_16x16x32_bf16 v[4:7], v[196:199], v[184:187], v[4:7]
	v_mfma_f32_16x16x32_bf16 v[0:3], v[200:203], v[184:187], v[0:3]
	s_waitcnt lgkmcnt(3)
	v_mfma_f32_16x16x32_bf16 v[64:67], v[220:223], v[204:207], v[64:67]
	s_waitcnt lgkmcnt(2)
	v_mfma_f32_16x16x32_bf16 v[76:79], v[224:227], v[204:207], v[76:79]
	s_waitcnt lgkmcnt(1)
	v_mfma_f32_16x16x32_bf16 v[72:75], v[228:231], v[204:207], v[72:75]
	s_waitcnt lgkmcnt(0)
	v_mfma_f32_16x16x32_bf16 v[68:71], v[232:235], v[204:207], v[68:71]
	v_mfma_f32_16x16x32_bf16 v[60:63], v[220:223], v[208:211], v[60:63]
	v_mfma_f32_16x16x32_bf16 v[56:59], v[224:227], v[208:211], v[56:59]
	v_mfma_f32_16x16x32_bf16 v[52:55], v[228:231], v[208:211], v[52:55]
	v_mfma_f32_16x16x32_bf16 v[48:51], v[232:235], v[208:211], v[48:51]
	v_mfma_f32_16x16x32_bf16 v[28:31], v[220:223], v[212:215], v[28:31]
	v_mfma_f32_16x16x32_bf16 v[24:27], v[224:227], v[212:215], v[24:27]
	v_mfma_f32_16x16x32_bf16 v[20:23], v[228:231], v[212:215], v[20:23]
	v_mfma_f32_16x16x32_bf16 v[16:19], v[232:235], v[212:215], v[16:19]
	v_mfma_f32_16x16x32_bf16 v[12:15], v[220:223], v[216:219], v[12:15]
	v_mfma_f32_16x16x32_bf16 v[8:11], v[224:227], v[216:219], v[8:11]
	v_mfma_f32_16x16x32_bf16 v[4:7], v[228:231], v[216:219], v[4:7]
	v_mfma_f32_16x16x32_bf16 v[0:3], v[232:235], v[216:219], v[0:3]
	s_andn2_b64 vcc, exec, s[20:21]
	s_cbranch_vccnz .LBB0_1359
	s_lshl_b32 s20, s47, 14
	s_xor_b32 s20, s20, 0x4000
	s_lshl_b32 s20, s20, 1
	s_add_i32 s20, s20, 0
	v_lshl_add_u32 v171, v161, 1, s20
	s_waitcnt vmcnt(7)
	v_cvt_pk_bf16_f32 v172, v141, v99
	v_cvt_pk_bf16_f32 v173, v119, v120
	v_cvt_pk_bf16_f32 v174, v121, v122
	v_cvt_pk_bf16_f32 v175, v123, v128
	v_lshl_add_u32 v171, v109, 1, s20
	ds_write_b128 v171, v[172:175] offset:16384
	v_cvt_pk_bf16_f32 v172, v130, v132
	v_cvt_pk_bf16_f32 v173, v133, v134
	v_cvt_pk_bf16_f32 v174, v135, v136
	v_cvt_pk_bf16_f32 v175, v137, v138
	v_lshl_add_u32 v171, v110, 1, s20
	ds_write_b128 v171, v[172:175] offset:16384
	v_cvt_pk_bf16_f32 v172, v139, v140
	v_cvt_pk_bf16_f32 v173, v142, v143
	v_cvt_pk_bf16_f32 v174, v144, v145
	v_cvt_pk_bf16_f32 v175, v146, v147
	v_lshl_add_u32 v171, v111, 1, s20
	ds_write_b128 v171, v[172:175] offset:16384
	s_waitcnt vmcnt(6)
	v_cvt_pk_bf16_f32 v172, v153, v154
	s_waitcnt vmcnt(4)
	v_cvt_pk_bf16_f32 v173, v155, v156
	s_waitcnt vmcnt(2)
	v_cvt_pk_bf16_f32 v174, v157, v158
	s_waitcnt vmcnt(0)
	v_cvt_pk_bf16_f32 v175, v159, v170
	v_lshl_add_u32 v171, v112, 1, s20
	ds_write_b128 v171, v[172:175] offset:16384
	s_branch .LBB0_1359
